# adds software-pipelined row loops (next row x/y prefetched into v100-v127) on top of half-tile GEMM round
# baseline (speedup 1.0000x reference)
; DI float bflo(unsigned u) { return __uint_as_float(u << 16); }
; DI float bfhi(unsigned u) { return __uint_as_float(u & 0xffff0000u); }
; DI int ltid() { int t = threadIdx.x; asm volatile("" : "+v"(t)); return t; }
; DI int lbid() { int b = blockIdx.x; asm volatile("" : "+s"(b)); return b; }
; DI void row_phase(const float* __restrict__ x_in, const u16* __restrict__ y, float c, const float* __restrict__ g_post,
;                   float* __restrict__ x_out, const float* __restrict__ g_pre, u16* __restrict__ hout) {
;   const int tid_ = ltid();
;   const int lane = tid_ & 63, wid = tid_ >> 6;
;   for (int row = lbid() * 8 + wid; row < S; row += gridDim.x * 8) {
;     f32x4 xv[4];
; #pragma unroll
;     for (int i = 0; i < 4; ++i) xv[i] = __builtin_nontemporal_load((const f32x4*)(x_in + (size_t)row * DM + 4 * lane + 256 * i));
;     if (y) {
;       f32x4 yv[4];
;       float ss = 0.f;
; #pragma unroll
;       for (int i = 0; i < 4; ++i) {
;         typedef unsigned u32x2_t __attribute__((ext_vector_type(2)));
;         const u32x2_t yb = __builtin_nontemporal_load((const u32x2_t*)(y + (size_t)row * DM + 4 * lane + 256 * i));
;         yv[i] = f32x4{bflo(yb.x), bfhi(yb.x), bflo(yb.y), bfhi(yb.y)};
;         ss += yv[i][0] * yv[i][0] + yv[i][1] * yv[i][1] + yv[i][2] * yv[i][2] + yv[i][3] * yv[i][3];
;       }
;       ss = wave_sum(ss);
;       float r = c * rsqrtf(ss * (1.f / DM) + EPS);
; #pragma unroll
;       for (int i = 0; i < 4; ++i) {
;         f32x4 g = *(const f32x4*)(g_post + 4 * lane + 256 * i);
;         xv[i] += yv[i] * g * r;
;         __builtin_nontemporal_store(xv[i], (f32x4*)(x_out + (size_t)row * DM + 4 * lane + 256 * i));
;       }
;     }
;     if (g_pre) {
;       float ss = 0.f;
; #pragma unroll
;       for (int i = 0; i < 4; ++i) ss += xv[i][0] * xv[i][0] + xv[i][1] * xv[i][1] + xv[i][2] * xv[i][2] + xv[i][3] * xv[i][3];
;       ss = wave_sum(ss);
;       float r = rsqrtf(ss * (1.f / DM) + EPS);
; #pragma unroll
;       for (int i = 0; i < 4; ++i) {
;         f32x4 g = *(const f32x4*)(g_pre + 4 * lane + 256 * i);
.LBB0_112:
	s_or_b64 exec, exec, s[0:1]
	v_mov_b32_e32 v0, v158
	s_mov_b32 s0, s91
	s_barrier
	s_nop 0
	v_ashrrev_i32_e32 v1, 6, v0
	v_lshl_add_u32 v32, s0, 3, v1
	s_movk_i32 s0, 0x4000
	v_cmp_gt_i32_e32 vcc, s0, v32
	s_and_saveexec_b64 s[0:1], vcc
	s_cbranch_execz .LBB0_115
	v_lshlrev_b32_e32 v0, 2, v0
	v_and_b32_e32 v33, 0xfc, v0
	v_lshlrev_b32_e32 v38, 2, v33
	v_mov_b32_e32 v39, 0
	v_lshl_add_u64 v[0:1], s[38:39], 0, v[38:39]
	s_mov_b64 s[2:3], 0x1000
	v_lshl_add_u64 v[34:35], v[0:1], 0, s[2:3]
	s_mov_b64 s[2:3], 0x2000
	v_lshl_add_u64 v[36:37], v[0:1], 0, s[2:3]
	s_movk_i32 s2, 0x2000
	v_add_co_u32_e32 v40, vcc, s2, v0
	s_lshl_b32 s4, s11, 3
	s_nop 0
	v_addc_co_u32_e32 v41, vcc, 0, v1, vcc
	global_load_dwordx4 v[0:3], v[34:35], off offset:1024
	global_load_dwordx4 v[4:7], v[34:35], off offset:2048
	global_load_dwordx4 v[8:11], v[40:41], off offset:-4096
	global_load_dwordx4 v[12:15], v[40:41], off
	global_load_dwordx4 v[16:19], v[34:35], off offset:3072
	global_load_dwordx4 v[20:23], v[36:37], off offset:1024
	global_load_dwordx4 v[24:27], v[36:37], off offset:2048
	global_load_dwordx4 v[28:31], v[36:37], off offset:3072
	v_lshlrev_b32_e32 v40, 1, v33
	v_mbcnt_hi_u32_b32 v33, -1, v144
	v_and_b32_e32 v42, 64, v33
	v_add_u32_e32 v42, 64, v42
	v_xor_b32_e32 v43, 32, v33
	v_cmp_lt_i32_e32 vcc, v43, v42
	v_mov_b32_e32 v41, v39
	v_lshl_add_u64 v[34:35], s[36:37], 0, v[38:39]
	v_cndmask_b32_e32 v43, v33, v43, vcc
	v_lshlrev_b32_e32 v44, 2, v43
	v_xor_b32_e32 v43, 16, v33
	v_cmp_lt_i32_e32 vcc, v43, v42
	v_lshl_add_u64 v[36:37], s[14:15], 0, v[40:41]
	v_lshl_add_u64 v[38:39], s[22:23], 0, v[38:39]
	v_cndmask_b32_e32 v43, v33, v43, vcc
	v_lshlrev_b32_e32 v45, 2, v43
	v_xor_b32_e32 v43, 8, v33
	v_cmp_lt_i32_e32 vcc, v43, v42
	v_lshl_add_u64 v[40:41], s[26:27], 0, v[40:41]
	s_mov_b64 s[2:3], 0
	v_cndmask_b32_e32 v43, v33, v43, vcc
	v_lshlrev_b32_e32 v46, 2, v43
	v_xor_b32_e32 v43, 4, v33
	v_cmp_lt_i32_e32 vcc, v43, v42
	v_mov_b32_e32 v50, 0x358637bd
	s_mov_b32 s5, 0x800000
	v_cndmask_b32_e32 v43, v33, v43, vcc
	v_lshlrev_b32_e32 v47, 2, v43
	v_xor_b32_e32 v43, 2, v33
	v_cmp_lt_i32_e32 vcc, v43, v42
	s_movk_i32 s6, 0x880
	s_movk_i32 s7, 0x3fff
	v_cndmask_b32_e32 v43, v33, v43, vcc
	v_lshlrev_b32_e32 v48, 2, v43
	v_xor_b32_e32 v43, 1, v33
	v_cmp_lt_i32_e32 vcc, v43, v42
	s_nop 1
	v_cndmask_b32_e32 v33, v33, v43, vcc
	v_lshlrev_b32_e32 v49, 2, v33
	v_mov_b32_e32 v124, v32
	v_ashrrev_i32_e32 v125, 31, v32
	v_lshlrev_b64 v[126:127], 11, v[124:125]
	v_lshl_add_u64 v[126:127], v[36:37], 0, v[126:127]
	global_load_dwordx2 v[100:101], v[126:127], off offset:512 nt
	global_load_dwordx2 v[102:103], v[126:127], off nt
	global_load_dwordx2 v[104:105], v[126:127], off offset:1536 nt
	global_load_dwordx2 v[106:107], v[126:127], off offset:1024 nt
	v_lshlrev_b64 v[126:127], 12, v[124:125]
	v_lshl_add_u64 v[126:127], v[34:35], 0, v[126:127]
	global_load_dwordx4 v[108:111], v[126:127], off nt
	global_load_dwordx4 v[112:115], v[126:127], off offset:1024 nt
	global_load_dwordx4 v[116:119], v[126:127], off offset:2048 nt
	global_load_dwordx4 v[120:123], v[126:127], off offset:3072 nt
	s_waitcnt vmcnt(0)
	s_branch .Lrow1_aw
.Lrow1_top:
	s_waitcnt vmcnt(8)
.Lrow1_aw:
	v_add_u32_e32 v124, s4, v32
	v_ashrrev_i32_e32 v33, 31, v32
	v_lshlrev_b64 v[42:43], 11, v[32:33]
	v_lshl_add_u64 v[42:43], v[36:37], 0, v[42:43]
	v_mov_b64_e32 v[68:69], v[100:101]
	v_mov_b64_e32 v[70:71], v[102:103]
	v_mov_b64_e32 v[72:73], v[104:105]
	v_mov_b64_e32 v[74:75], v[106:107]
	v_lshlrev_b64 v[42:43], 12, v[32:33]
	v_lshl_add_u64 v[76:77], v[34:35], 0, v[42:43]
	v_mov_b64_e32 v[52:53], v[108:109]
	v_mov_b64_e32 v[54:55], v[110:111]
	v_mov_b64_e32 v[56:57], v[112:113]
	v_mov_b64_e32 v[58:59], v[114:115]
	v_mov_b64_e32 v[60:61], v[116:117]
	v_mov_b64_e32 v[62:63], v[118:119]
	v_mov_b64_e32 v[64:65], v[120:121]
	v_mov_b64_e32 v[66:67], v[122:123]
	v_lshrrev_b32_e32 v125, 8, v124
	v_cmp_gt_u32_e64 s[98:99], 64, v125
	s_and_saveexec_b64 s[98:99], s[98:99]
	s_cbranch_execz .Lrow1_nopf
	v_ashrrev_i32_e32 v125, 31, v124
	v_lshlrev_b64 v[126:127], 11, v[124:125]
	v_lshl_add_u64 v[126:127], v[36:37], 0, v[126:127]
	global_load_dwordx2 v[100:101], v[126:127], off offset:512 nt
	global_load_dwordx2 v[102:103], v[126:127], off nt
	global_load_dwordx2 v[104:105], v[126:127], off offset:1536 nt
	global_load_dwordx2 v[106:107], v[126:127], off offset:1024 nt
	v_lshlrev_b64 v[126:127], 12, v[124:125]
	v_lshl_add_u64 v[126:127], v[34:35], 0, v[126:127]
	global_load_dwordx4 v[108:111], v[126:127], off nt
	global_load_dwordx4 v[112:115], v[126:127], off offset:1024 nt
	global_load_dwordx4 v[116:119], v[126:127], off offset:2048 nt
	global_load_dwordx4 v[120:123], v[126:127], off offset:3072 nt
; DI float bflo(unsigned u) { return __uint_as_float(u << 16); }
; DI float bfhi(unsigned u) { return __uint_as_float(u & 0xffff0000u); }
; DI void row_phase(const float* __restrict__ x_in, const u16* __restrict__ y, float c, const float* __restrict__ g_post,
;                   float* __restrict__ x_out, const float* __restrict__ g_pre, u16* __restrict__ hout) {
;     ...
;         yv[i] = f32x4{bflo(yb.x), bfhi(yb.x), bflo(yb.y), bfhi(yb.y)};
;         ss += yv[i][0] * yv[i][0] + yv[i][1] * yv[i][1] + yv[i][2] * yv[i][2] + yv[i][3] * yv[i][3];
;       }
;       ss = wave_sum(ss);
;       float r = c * rsqrtf(ss * (1.f / DM) + EPS);
; #pragma unroll
;       for (int i = 0; i < 4; ++i) {
;         f32x4 g = *(const f32x4*)(g_post + 4 * lane + 256 * i);
;         xv[i] += yv[i] * g * r;
;         __builtin_nontemporal_store(xv[i], (f32x4*)(x_out + (size_t)row * DM + 4 * lane + 256 * i));
;       }
;     }
;     if (g_pre) {
;       float ss = 0.f;
; #pragma unroll
;       for (int i = 0; i < 4; ++i) ss += xv[i][0] * xv[i][0] + xv[i][1] * xv[i][1] + xv[i][2] * xv[i][2] + xv[i][3] * xv[i][3];
;       ss = wave_sum(ss);
;       float r = rsqrtf(ss * (1.f / DM) + EPS);
; #pragma unroll
;       for (int i = 0; i < 4; ++i) {
;         f32x4 g = *(const f32x4*)(g_pre + 4 * lane + 256 * i);
;         f32x4 hv = xv[i] * g * r;
;         uint2 o = {pack2(hv[0], hv[1]), pack2(hv[2], hv[3])};
;         *(uint2*)(hout + (size_t)row * LDH + 4 * lane + 256 * i) = o;
;       }
.Lrow1_nopf:
	s_or_b64 exec, exec, s[98:99]
	v_lshl_add_u64 v[42:43], v[38:39], 0, v[42:43]
	v_and_b32_e32 v79, 0xffff0000, v68
	v_and_b32_e32 v78, 0xffff0000, v70
	v_lshlrev_b32_e32 v77, 16, v68
	v_lshlrev_b32_e32 v76, 16, v70
	v_lshlrev_b32_e32 v80, 16, v71
	v_and_b32_e32 v68, 0xffff0000, v71
	v_lshlrev_b32_e32 v71, 16, v72
	v_lshlrev_b32_e32 v70, 16, v74
	v_and_b32_e32 v83, 0xffff0000, v72
	v_and_b32_e32 v82, 0xffff0000, v74
	v_lshlrev_b32_e32 v84, 16, v75
	v_and_b32_e32 v72, 0xffff0000, v75
	v_pk_mul_f32 v[74:75], v[78:79], v[78:79]
	v_lshlrev_b32_e32 v81, 16, v69
	v_pk_mul_f32 v[86:87], v[82:83], v[82:83]
	v_pk_fma_f32 v[74:75], v[76:77], v[76:77], v[74:75]
	v_and_b32_e32 v69, 0xffff0000, v69
	v_lshlrev_b32_e32 v85, 16, v73
	v_pk_fma_f32 v[86:87], v[70:71], v[70:71], v[86:87]
	v_pk_fma_f32 v[74:75], v[80:81], v[80:81], v[74:75]
	v_and_b32_e32 v73, 0xffff0000, v73
	v_pk_fma_f32 v[86:87], v[84:85], v[84:85], v[86:87]
	v_pk_fma_f32 v[74:75], v[68:69], v[68:69], v[74:75]
	v_pk_fma_f32 v[86:87], v[72:73], v[72:73], v[86:87]
	v_add_f32_e32 v33, v74, v75
	v_add_f32_e32 v33, v33, v86
	v_add_f32_e32 v33, v33, v87
	ds_bpermute_b32 v51, v44, v33
	v_mov_b32_e32 v74, v76
	v_mov_b32_e32 v75, v78
	v_mov_b32_e32 v78, v77
	v_mov_b32_e32 v86, v80
	s_waitcnt lgkmcnt(0)
	v_add_f32_e32 v33, v33, v51
	ds_bpermute_b32 v51, v45, v33
	v_mov_b32_e32 v76, v70
	v_mov_b32_e32 v77, v82
	v_mov_b32_e32 v82, v71
	v_pk_mul_f32 v[70:71], v[8:9], v[74:75]
	s_waitcnt lgkmcnt(0)
	v_add_f32_e32 v33, v33, v51
	ds_bpermute_b32 v51, v46, v33
	v_pk_mul_f32 v[78:79], v[0:1], v[78:79]
	v_mov_b32_e32 v87, v68
	v_pk_mul_f32 v[76:77], v[4:5], v[76:77]
	v_pk_mul_f32 v[82:83], v[16:17], v[82:83]
	s_waitcnt lgkmcnt(0)
	v_add_f32_e32 v33, v33, v51
	ds_bpermute_b32 v51, v47, v33
	v_mov_b32_e32 v68, v81
	v_mov_b32_e32 v88, v84
	v_mov_b32_e32 v89, v72
	v_pk_mul_f32 v[74:75], v[10:11], v[86:87]
	s_waitcnt lgkmcnt(0)
	v_add_f32_e32 v33, v33, v51
	ds_bpermute_b32 v51, v48, v33
	v_mov_b32_e32 v72, v85
	v_pk_mul_f32 v[68:69], v[2:3], v[68:69]
	v_pk_mul_f32 v[86:87], v[6:7], v[88:89]
	v_pk_mul_f32 v[72:73], v[18:19], v[72:73]
	s_waitcnt lgkmcnt(0)
	v_add_f32_e32 v33, v33, v51
	ds_bpermute_b32 v51, v49, v33
	s_waitcnt lgkmcnt(0)
	v_add_f32_e32 v33, v33, v51
	v_fmamk_f32 v33, v33, 0x3a800000, v50
	v_mul_f32_e32 v51, 0x4b800000, v33
	v_cmp_gt_f32_e32 vcc, s5, v33
	s_nop 1
	v_cndmask_b32_e32 v33, v33, v51, vcc
	v_rsq_f32_e32 v33, v33
	s_nop 0
	v_mul_f32_e32 v51, 0x45800000, v33
	v_cndmask_b32_e32 v33, v33, v51, vcc
	v_mul_f32_e32 v80, 0.5, v33
	v_pk_fma_f32 v[52:53], v[70:71], v[80:81], v[52:53] op_sel_hi:[1,0,1]
	v_pk_fma_f32 v[56:57], v[78:79], v[80:81], v[56:57] op_sel_hi:[1,0,1]
	v_pk_fma_f32 v[60:61], v[76:77], v[80:81], v[60:61] op_sel_hi:[1,0,1]
	v_pk_fma_f32 v[64:65], v[82:83], v[80:81], v[64:65] op_sel_hi:[1,0,1]
	v_mov_b32_e32 v70, v53
	v_mov_b32_e32 v71, v57
	v_pk_fma_f32 v[54:55], v[74:75], v[80:81], v[54:55] op_sel_hi:[1,0,1]
	v_pk_fma_f32 v[58:59], v[68:69], v[80:81], v[58:59] op_sel_hi:[1,0,1]
	v_mov_b32_e32 v68, v52
	v_mov_b32_e32 v69, v56
	v_mov_b32_e32 v78, v65
	v_mov_b32_e32 v79, v61
	v_pk_mul_f32 v[70:71], v[70:71], v[70:71]
	v_pk_fma_f32 v[62:63], v[86:87], v[80:81], v[62:63] op_sel_hi:[1,0,1]
	v_pk_fma_f32 v[66:67], v[72:73], v[80:81], v[66:67] op_sel_hi:[1,0,1]
	v_mov_b32_e32 v72, v54
	v_mov_b32_e32 v73, v58
	v_mov_b32_e32 v76, v64
	v_mov_b32_e32 v77, v60
	v_pk_mul_f32 v[78:79], v[78:79], v[78:79]
	v_pk_fma_f32 v[68:69], v[68:69], v[68:69], v[70:71]
	v_mov_b32_e32 v74, v55
	v_mov_b32_e32 v75, v59
	v_mov_b32_e32 v80, v66
	v_mov_b32_e32 v81, v62
	v_pk_fma_f32 v[70:71], v[76:77], v[76:77], v[78:79]
	v_pk_fma_f32 v[68:69], v[72:73], v[72:73], v[68:69]
	v_mov_b32_e32 v82, v67
	v_mov_b32_e32 v83, v63
	v_pk_fma_f32 v[70:71], v[80:81], v[80:81], v[70:71]
	v_pk_fma_f32 v[68:69], v[74:75], v[74:75], v[68:69]
	v_pk_fma_f32 v[70:71], v[82:83], v[82:83], v[70:71]
	v_add_f32_e32 v33, v68, v69
	v_add_f32_e32 v33, v71, v33
	v_add_f32_e32 v33, v70, v33
	ds_bpermute_b32 v51, v44, v33
	v_mad_i64_i32 v[68:69], s[16:17], v32, s6, v[40:41]
	v_add_u32_e32 v32, s4, v32
	v_cmp_lt_i32_e32 vcc, s7, v32
	s_waitcnt lgkmcnt(0)
	v_add_f32_e32 v33, v33, v51
	ds_bpermute_b32 v51, v45, v33
	s_or_b64 s[2:3], vcc, s[2:3]
	global_store_dwordx4 v[42:43], v[52:55], off nt
	global_store_dwordx4 v[42:43], v[56:59], off offset:1024 nt
	global_store_dwordx4 v[42:43], v[60:63], off offset:2048 nt
	global_store_dwordx4 v[42:43], v[64:67], off offset:3072 nt
	v_pk_mul_f32 v[42:43], v[12:13], v[52:53]
	s_waitcnt lgkmcnt(0)
	v_add_f32_e32 v33, v33, v51
	ds_bpermute_b32 v51, v46, v33
	v_pk_mul_f32 v[52:53], v[14:15], v[54:55]
	v_pk_mul_f32 v[54:55], v[20:21], v[56:57]
	v_pk_mul_f32 v[56:57], v[22:23], v[58:59]
	v_pk_mul_f32 v[58:59], v[24:25], v[60:61]
	s_waitcnt lgkmcnt(0)
	v_add_f32_e32 v33, v33, v51
	ds_bpermute_b32 v51, v47, v33
	v_pk_mul_f32 v[60:61], v[26:27], v[62:63]
	v_pk_mul_f32 v[62:63], v[28:29], v[64:65]
	v_pk_mul_f32 v[64:65], v[30:31], v[66:67]
	s_waitcnt lgkmcnt(0)
	v_add_f32_e32 v33, v33, v51
	ds_bpermute_b32 v51, v48, v33
	s_waitcnt lgkmcnt(0)
	v_add_f32_e32 v33, v33, v51
	ds_bpermute_b32 v51, v49, v33
	s_waitcnt lgkmcnt(0)
	v_add_f32_e32 v33, v33, v51
	v_fmamk_f32 v33, v33, 0x3a800000, v50
	v_mul_f32_e32 v51, 0x4b800000, v33
	v_cmp_gt_f32_e32 vcc, s5, v33
	s_nop 1
	v_cndmask_b32_e32 v33, v33, v51, vcc
	v_rsq_f32_e32 v33, v33
	s_nop 0
	v_mul_f32_e32 v51, 0x45800000, v33
	v_cndmask_b32_e32 v66, v33, v51, vcc
	v_pk_mul_f32 v[52:53], v[52:53], v[66:67] op_sel_hi:[1,0]
	v_pk_mul_f32 v[42:43], v[42:43], v[66:67] op_sel_hi:[1,0]
	v_pk_mul_f32 v[56:57], v[56:57], v[66:67] op_sel_hi:[1,0]
	v_pk_mul_f32 v[54:55], v[54:55], v[66:67] op_sel_hi:[1,0]
	v_pk_mul_f32 v[60:61], v[60:61], v[66:67] op_sel_hi:[1,0]
	v_pk_mul_f32 v[58:59], v[58:59], v[66:67] op_sel_hi:[1,0]
	v_pk_mul_f32 v[64:65], v[64:65], v[66:67] op_sel_hi:[1,0]
	v_pk_mul_f32 v[62:63], v[62:63], v[66:67] op_sel_hi:[1,0]
	v_cvt_pk_bf16_f32 v42, v42, v43
	v_cvt_pk_bf16_f32 v43, v52, v53
	v_cvt_pk_bf16_f32 v52, v54, v55
	v_cvt_pk_bf16_f32 v53, v56, v57
	v_cvt_pk_bf16_f32 v54, v58, v59
	v_cvt_pk_bf16_f32 v55, v60, v61
	v_cvt_pk_bf16_f32 v56, v62, v63
	v_cvt_pk_bf16_f32 v57, v64, v65
	global_store_dwordx2 v[68:69], v[42:43], off
	global_store_dwordx2 v[68:69], v[52:53], off offset:512
	global_store_dwordx2 v[68:69], v[54:55], off offset:1024
	global_store_dwordx2 v[68:69], v[56:57], off offset:1536
	s_andn2_b64 exec, exec, s[2:3]
	s_cbranch_execnz .Lrow1_top

; DI float bflo(unsigned u) { return __uint_as_float(u << 16); }
; DI float bfhi(unsigned u) { return __uint_as_float(u & 0xffff0000u); }
; DI int ltid() { int t = threadIdx.x; asm volatile("" : "+v"(t)); return t; }
; DI int lbid() { int b = blockIdx.x; asm volatile("" : "+s"(b)); return b; }
; DI void row_phase(const float* __restrict__ x_in, const u16* __restrict__ y, float c, const float* __restrict__ g_post,
;                   float* __restrict__ x_out, const float* __restrict__ g_pre, u16* __restrict__ hout) {
;   const int tid_ = ltid();
;   const int lane = tid_ & 63, wid = tid_ >> 6;
;   for (int row = lbid() * 8 + wid; row < S; row += gridDim.x * 8) {
;     f32x4 xv[4];
; #pragma unroll
;     for (int i = 0; i < 4; ++i) xv[i] = __builtin_nontemporal_load((const f32x4*)(x_in + (size_t)row * DM + 4 * lane + 256 * i));
;     if (y) {
;       f32x4 yv[4];
;       float ss = 0.f;
; #pragma unroll
;       for (int i = 0; i < 4; ++i) {
;         typedef unsigned u32x2_t __attribute__((ext_vector_type(2)));
;         const u32x2_t yb = __builtin_nontemporal_load((const u32x2_t*)(y + (size_t)row * DM + 4 * lane + 256 * i));
;         yv[i] = f32x4{bflo(yb.x), bfhi(yb.x), bflo(yb.y), bfhi(yb.y)};
;         ss += yv[i][0] * yv[i][0] + yv[i][1] * yv[i][1] + yv[i][2] * yv[i][2] + yv[i][3] * yv[i][3];
;       }
;       ss = wave_sum(ss);
;       float r = c * rsqrtf(ss * (1.f / DM) + EPS);
; #pragma unroll
;       for (int i = 0; i < 4; ++i) {
;         f32x4 g = *(const f32x4*)(g_post + 4 * lane + 256 * i);
;         xv[i] += yv[i] * g * r;
;         __builtin_nontemporal_store(xv[i], (f32x4*)(x_out + (size_t)row * DM + 4 * lane + 256 * i));
;       }
;     }
;     if (g_pre) {
;       float ss = 0.f;
; #pragma unroll
;       for (int i = 0; i < 4; ++i) ss += xv[i][0] * xv[i][0] + xv[i][1] * xv[i][1] + xv[i][2] * xv[i][2] + xv[i][3] * xv[i][3];
;       ss = wave_sum(ss);
;       float r = rsqrtf(ss * (1.f / DM) + EPS);
; #pragma unroll
;       for (int i = 0; i < 4; ++i) {
;         f32x4 g = *(const f32x4*)(g_pre + 4 * lane + 256 * i);
.LBB0_327:
	s_or_b64 exec, exec, s[0:1]
	v_mov_b32_e32 v0, v158
	s_barrier
	s_mov_b32 s0, s92
	v_ashrrev_i32_e32 v1, 6, v0
	s_movk_i32 s2, 0x4000
	v_lshl_add_u32 v32, s0, 3, v1
	v_cmp_gt_i32_e32 vcc, s2, v32
	s_and_saveexec_b64 s[0:1], vcc
	s_cbranch_execz .LBB0_330
	v_lshlrev_b32_e32 v0, 2, v0
	v_and_b32_e32 v33, 0xfc, v0
	v_lshlrev_b32_e32 v36, 2, v33
	v_mov_b32_e32 v37, 0
	v_lshl_add_u64 v[0:1], s[38:39], 0, v[36:37]
	s_mov_b64 s[4:5], 0x3000
	v_lshl_add_u64 v[34:35], v[0:1], 0, s[4:5]
	s_mov_b64 s[4:5], 0x4000
	v_add_co_u32_e32 v40, vcc, s2, v0
	v_lshl_add_u64 v[38:39], v[0:1], 0, s[4:5]
	s_nop 0
	v_addc_co_u32_e32 v41, vcc, 0, v1, vcc
	global_load_dwordx4 v[0:3], v[34:35], off offset:1024
	global_load_dwordx4 v[4:7], v[34:35], off offset:2048
	global_load_dwordx4 v[8:11], v[40:41], off offset:-4096
	global_load_dwordx4 v[12:15], v[40:41], off
	global_load_dwordx4 v[16:19], v[34:35], off offset:3072
	global_load_dwordx4 v[20:23], v[38:39], off offset:1024
	global_load_dwordx4 v[24:27], v[38:39], off offset:2048
	global_load_dwordx4 v[28:31], v[38:39], off offset:3072
	v_lshlrev_b32_e32 v38, 1, v33
	v_mov_b32_e32 v39, v37
	v_lshl_add_u64 v[34:35], s[22:23], 0, v[36:37]
	v_lshl_add_u64 v[36:37], s[14:15], 0, v[38:39]
	v_lshl_add_u64 v[38:39], s[26:27], 0, v[38:39]
	s_lshl_b32 s4, s11, 3
	s_mov_b64 s[2:3], 0
	v_mov_b32_e32 v42, 0x358637bd
	s_mov_b32 s5, 0x800000
	s_movk_i32 s6, 0x880
	s_movk_i32 s7, 0x3fff
	v_mov_b32_e32 v124, v32
	v_ashrrev_i32_e32 v125, 31, v32
	v_lshlrev_b64 v[126:127], 11, v[124:125]
	v_lshl_add_u64 v[126:127], v[36:37], 0, v[126:127]
	global_load_dwordx2 v[100:101], v[126:127], off offset:512 nt
	global_load_dwordx2 v[102:103], v[126:127], off nt
	global_load_dwordx2 v[104:105], v[126:127], off offset:1536 nt
	global_load_dwordx2 v[106:107], v[126:127], off offset:1024 nt
	v_lshlrev_b64 v[126:127], 12, v[124:125]
	v_lshl_add_u64 v[126:127], v[34:35], 0, v[126:127]
	global_load_dwordx4 v[108:111], v[126:127], off nt
	global_load_dwordx4 v[112:115], v[126:127], off offset:1024 nt
	global_load_dwordx4 v[116:119], v[126:127], off offset:2048 nt
	global_load_dwordx4 v[120:123], v[126:127], off offset:3072 nt
	s_waitcnt vmcnt(0)
	s_branch .Lrow2_aw

; DI int lbid() { int b = blockIdx.x; asm volatile("" : "+s"(b)); return b; }
; DI void row_phase(const float* __restrict__ x_in, const u16* __restrict__ y, float c, const float* __restrict__ g_post,
;                   float* __restrict__ x_out, const float* __restrict__ g_pre, u16* __restrict__ hout) {
;     ...
;   for (int row = lbid() * 8 + wid; row < S; row += gridDim.x * 8) {
;     f32x4 xv[4];
; #pragma unroll
;     for (int i = 0; i < 4; ++i) xv[i] = __builtin_nontemporal_load((const f32x4*)(x_in + (size_t)row * DM + 4 * lane + 256 * i));
;     if (y) {
;       f32x4 yv[4];
;       float ss = 0.f;
; #pragma unroll
;       for (int i = 0; i < 4; ++i) {
;         typedef unsigned u32x2_t __attribute__((ext_vector_type(2)));
;         const u32x2_t yb = __builtin_nontemporal_load((const u32x2_t*)(y + (size_t)row * DM + 4 * lane + 256 * i));
.Lrow2_aw:
	v_add_u32_e32 v124, s4, v32
	v_ashrrev_i32_e32 v33, 31, v32
	v_lshlrev_b64 v[40:41], 11, v[32:33]
	v_lshl_add_u64 v[40:41], v[36:37], 0, v[40:41]
	v_mov_b64_e32 v[60:61], v[100:101]
	v_mov_b64_e32 v[62:63], v[102:103]
	v_mov_b64_e32 v[64:65], v[104:105]
	v_mov_b64_e32 v[66:67], v[106:107]
	v_lshlrev_b64 v[40:41], 12, v[32:33]
	v_lshl_add_u64 v[40:41], v[34:35], 0, v[40:41]
	v_mov_b64_e32 v[44:45], v[108:109]
	v_mov_b64_e32 v[46:47], v[110:111]
	v_mov_b64_e32 v[48:49], v[112:113]
	v_mov_b64_e32 v[50:51], v[114:115]
	v_mov_b64_e32 v[52:53], v[116:117]
	v_mov_b64_e32 v[54:55], v[118:119]
	v_mov_b64_e32 v[56:57], v[120:121]
	v_mov_b64_e32 v[58:59], v[122:123]
	v_lshrrev_b32_e32 v125, 8, v124
	v_cmp_gt_u32_e64 s[98:99], 64, v125
	s_and_saveexec_b64 s[98:99], s[98:99]
	s_cbranch_execz .Lrow2_nopf
	v_ashrrev_i32_e32 v125, 31, v124
	v_lshlrev_b64 v[126:127], 11, v[124:125]
	v_lshl_add_u64 v[126:127], v[36:37], 0, v[126:127]
	global_load_dwordx2 v[100:101], v[126:127], off offset:512 nt
	global_load_dwordx2 v[102:103], v[126:127], off nt
	global_load_dwordx2 v[104:105], v[126:127], off offset:1536 nt
	global_load_dwordx2 v[106:107], v[126:127], off offset:1024 nt
	v_lshlrev_b64 v[126:127], 12, v[124:125]
	v_lshl_add_u64 v[126:127], v[34:35], 0, v[126:127]
	global_load_dwordx4 v[108:111], v[126:127], off nt
	global_load_dwordx4 v[112:115], v[126:127], off offset:1024 nt
	global_load_dwordx4 v[116:119], v[126:127], off offset:2048 nt
	global_load_dwordx4 v[120:123], v[126:127], off offset:3072 nt
; DI float bflo(unsigned u) { return __uint_as_float(u << 16); }
; DI float bfhi(unsigned u) { return __uint_as_float(u & 0xffff0000u); }
; DI void row_phase(const float* __restrict__ x_in, const u16* __restrict__ y, float c, const float* __restrict__ g_post,
;                   float* __restrict__ x_out, const float* __restrict__ g_pre, u16* __restrict__ hout) {
;     ...
;         yv[i] = f32x4{bflo(yb.x), bfhi(yb.x), bflo(yb.y), bfhi(yb.y)};
;         ss += yv[i][0] * yv[i][0] + yv[i][1] * yv[i][1] + yv[i][2] * yv[i][2] + yv[i][3] * yv[i][3];
;       }
;       ss = wave_sum(ss);
;       float r = c * rsqrtf(ss * (1.f / DM) + EPS);
; #pragma unroll
;       for (int i = 0; i < 4; ++i) {
;         f32x4 g = *(const f32x4*)(g_post + 4 * lane + 256 * i);
;         xv[i] += yv[i] * g * r;
;         __builtin_nontemporal_store(xv[i], (f32x4*)(x_out + (size_t)row * DM + 4 * lane + 256 * i));
;       }
;     }
;     if (g_pre) {
;       float ss = 0.f;
; #pragma unroll
;       for (int i = 0; i < 4; ++i) ss += xv[i][0] * xv[i][0] + xv[i][1] * xv[i][1] + xv[i][2] * xv[i][2] + xv[i][3] * xv[i][3];
;       ss = wave_sum(ss);
;       float r = rsqrtf(ss * (1.f / DM) + EPS);
; #pragma unroll
;       for (int i = 0; i < 4; ++i) {
;         f32x4 g = *(const f32x4*)(g_pre + 4 * lane + 256 * i);
;         f32x4 hv = xv[i] * g * r;
;         uint2 o = {pack2(hv[0], hv[1]), pack2(hv[2], hv[3])};
;         *(uint2*)(hout + (size_t)row * LDH + 4 * lane + 256 * i) = o;
;       }
.Lrow2_nopf:
	s_or_b64 exec, exec, s[98:99]
	v_and_b32_e32 v71, 0xffff0000, v60
	v_and_b32_e32 v70, 0xffff0000, v62
	v_lshlrev_b32_e32 v69, 16, v60
	v_lshlrev_b32_e32 v68, 16, v62
	v_lshlrev_b32_e32 v72, 16, v63
	v_and_b32_e32 v60, 0xffff0000, v63
	v_lshlrev_b32_e32 v63, 16, v64
	v_lshlrev_b32_e32 v62, 16, v66
	v_and_b32_e32 v75, 0xffff0000, v64
	v_and_b32_e32 v74, 0xffff0000, v66
	v_lshlrev_b32_e32 v76, 16, v67
	v_and_b32_e32 v64, 0xffff0000, v67
	v_pk_mul_f32 v[66:67], v[70:71], v[70:71]
	v_lshlrev_b32_e32 v73, 16, v61
	v_pk_mul_f32 v[78:79], v[74:75], v[74:75]
	v_pk_fma_f32 v[66:67], v[68:69], v[68:69], v[66:67]
	v_and_b32_e32 v61, 0xffff0000, v61
	v_lshlrev_b32_e32 v77, 16, v65
	v_pk_fma_f32 v[78:79], v[62:63], v[62:63], v[78:79]
	v_pk_fma_f32 v[66:67], v[72:73], v[72:73], v[66:67]
	v_and_b32_e32 v65, 0xffff0000, v65
	v_pk_fma_f32 v[78:79], v[76:77], v[76:77], v[78:79]
	v_pk_fma_f32 v[66:67], v[60:61], v[60:61], v[66:67]
	v_pk_fma_f32 v[78:79], v[64:65], v[64:65], v[78:79]
	v_add_f32_e32 v33, v66, v67
	v_add_f32_e32 v33, v33, v78
	v_add_f32_e32 v33, v33, v79
	ds_bpermute_b32 v43, v159, v33
	v_mov_b32_e32 v66, v68
	v_mov_b32_e32 v67, v70
	v_mov_b32_e32 v70, v69
	v_mov_b32_e32 v78, v72
	s_waitcnt lgkmcnt(0)
	v_add_f32_e32 v33, v33, v43
	ds_bpermute_b32 v43, v160, v33
	v_mov_b32_e32 v68, v62
	v_mov_b32_e32 v69, v74
	v_mov_b32_e32 v74, v63
	v_pk_mul_f32 v[62:63], v[8:9], v[66:67]
	s_waitcnt lgkmcnt(0)
	v_add_f32_e32 v33, v33, v43
	ds_bpermute_b32 v43, v161, v33
	v_pk_mul_f32 v[70:71], v[0:1], v[70:71]
	v_mov_b32_e32 v79, v60
	v_pk_mul_f32 v[68:69], v[4:5], v[68:69]
	v_pk_mul_f32 v[74:75], v[16:17], v[74:75]
	s_waitcnt lgkmcnt(0)
	v_add_f32_e32 v33, v33, v43
	ds_bpermute_b32 v43, v162, v33
	v_mov_b32_e32 v60, v73
	v_mov_b32_e32 v80, v76
	v_mov_b32_e32 v81, v64
	v_pk_mul_f32 v[66:67], v[10:11], v[78:79]
	s_waitcnt lgkmcnt(0)
	v_add_f32_e32 v33, v33, v43
	ds_bpermute_b32 v43, v163, v33
	v_mov_b32_e32 v64, v77
	v_pk_mul_f32 v[60:61], v[2:3], v[60:61]
	v_pk_mul_f32 v[78:79], v[6:7], v[80:81]
	v_pk_mul_f32 v[64:65], v[18:19], v[64:65]
	s_waitcnt lgkmcnt(0)
	v_add_f32_e32 v33, v33, v43
	ds_bpermute_b32 v43, v164, v33
	s_waitcnt lgkmcnt(0)
	v_add_f32_e32 v33, v33, v43
	v_fmamk_f32 v33, v33, 0x3a800000, v42
	v_mul_f32_e32 v43, 0x4b800000, v33
	v_cmp_gt_f32_e32 vcc, s5, v33
	s_nop 1
	v_cndmask_b32_e32 v33, v33, v43, vcc
	v_rsq_f32_e32 v33, v33
	s_nop 0
	v_mul_f32_e32 v43, 0x45800000, v33
	v_cndmask_b32_e32 v72, v33, v43, vcc
	v_pk_fma_f32 v[44:45], v[62:63], v[72:73], v[44:45] op_sel_hi:[1,0,1]
	v_pk_fma_f32 v[48:49], v[70:71], v[72:73], v[48:49] op_sel_hi:[1,0,1]
	v_pk_fma_f32 v[52:53], v[68:69], v[72:73], v[52:53] op_sel_hi:[1,0,1]
	v_pk_fma_f32 v[56:57], v[74:75], v[72:73], v[56:57] op_sel_hi:[1,0,1]
	v_mov_b32_e32 v62, v45
	v_mov_b32_e32 v63, v49
	v_pk_fma_f32 v[46:47], v[66:67], v[72:73], v[46:47] op_sel_hi:[1,0,1]
	v_pk_fma_f32 v[50:51], v[60:61], v[72:73], v[50:51] op_sel_hi:[1,0,1]
	v_mov_b32_e32 v60, v44
	v_mov_b32_e32 v61, v48
	v_mov_b32_e32 v70, v57
	v_mov_b32_e32 v71, v53
	v_pk_mul_f32 v[62:63], v[62:63], v[62:63]
	v_pk_fma_f32 v[54:55], v[78:79], v[72:73], v[54:55] op_sel_hi:[1,0,1]
	v_pk_fma_f32 v[58:59], v[64:65], v[72:73], v[58:59] op_sel_hi:[1,0,1]
	v_mov_b32_e32 v64, v46
	v_mov_b32_e32 v65, v50
	v_mov_b32_e32 v68, v56
	v_mov_b32_e32 v69, v52
	v_pk_mul_f32 v[70:71], v[70:71], v[70:71]
	v_pk_fma_f32 v[60:61], v[60:61], v[60:61], v[62:63]
	v_mov_b32_e32 v66, v47
	v_mov_b32_e32 v67, v51
	v_mov_b32_e32 v72, v58
	v_mov_b32_e32 v73, v54
	v_pk_fma_f32 v[62:63], v[68:69], v[68:69], v[70:71]
	v_pk_fma_f32 v[60:61], v[64:65], v[64:65], v[60:61]
	v_mov_b32_e32 v74, v59
	v_mov_b32_e32 v75, v55
	v_pk_fma_f32 v[62:63], v[72:73], v[72:73], v[62:63]
	v_pk_fma_f32 v[60:61], v[66:67], v[66:67], v[60:61]
	v_pk_fma_f32 v[62:63], v[74:75], v[74:75], v[62:63]
	v_add_f32_e32 v33, v60, v61
	v_add_f32_e32 v33, v63, v33
	v_add_f32_e32 v33, v62, v33
	ds_bpermute_b32 v43, v159, v33
	v_mad_i64_i32 v[60:61], s[34:35], v32, s6, v[38:39]
	v_add_u32_e32 v32, s4, v32
	v_cmp_lt_i32_e32 vcc, s7, v32
	s_waitcnt lgkmcnt(0)
	v_add_f32_e32 v33, v33, v43
	ds_bpermute_b32 v43, v160, v33
	s_or_b64 s[2:3], vcc, s[2:3]
	global_store_dwordx4 v[40:41], v[44:47], off nt
	global_store_dwordx4 v[40:41], v[48:51], off offset:1024 nt
	global_store_dwordx4 v[40:41], v[52:55], off offset:2048 nt
	global_store_dwordx4 v[40:41], v[56:59], off offset:3072 nt
	v_pk_mul_f32 v[40:41], v[12:13], v[44:45]
	s_waitcnt lgkmcnt(0)
	v_add_f32_e32 v33, v33, v43
	ds_bpermute_b32 v43, v161, v33
	v_pk_mul_f32 v[44:45], v[14:15], v[46:47]
	v_pk_mul_f32 v[46:47], v[20:21], v[48:49]
	v_pk_mul_f32 v[48:49], v[22:23], v[50:51]
	v_pk_mul_f32 v[50:51], v[24:25], v[52:53]
	s_waitcnt lgkmcnt(0)
	v_add_f32_e32 v33, v33, v43
	ds_bpermute_b32 v43, v162, v33
	v_pk_mul_f32 v[52:53], v[26:27], v[54:55]
	v_pk_mul_f32 v[54:55], v[28:29], v[56:57]
	v_pk_mul_f32 v[56:57], v[30:31], v[58:59]
	s_waitcnt lgkmcnt(0)
	v_add_f32_e32 v33, v33, v43
	ds_bpermute_b32 v43, v163, v33
	s_waitcnt lgkmcnt(0)
	v_add_f32_e32 v33, v33, v43
	ds_bpermute_b32 v43, v164, v33
	s_waitcnt lgkmcnt(0)
	v_add_f32_e32 v33, v33, v43
	v_fmamk_f32 v33, v33, 0x3a800000, v42
	v_mul_f32_e32 v43, 0x4b800000, v33
	v_cmp_gt_f32_e32 vcc, s5, v33
	s_nop 1
	v_cndmask_b32_e32 v33, v33, v43, vcc
	v_rsq_f32_e32 v33, v33
	s_nop 0
	v_mul_f32_e32 v43, 0x45800000, v33
	v_cndmask_b32_e32 v58, v33, v43, vcc
	v_pk_mul_f32 v[44:45], v[44:45], v[58:59] op_sel_hi:[1,0]
	v_pk_mul_f32 v[40:41], v[40:41], v[58:59] op_sel_hi:[1,0]
	v_pk_mul_f32 v[48:49], v[48:49], v[58:59] op_sel_hi:[1,0]
	v_pk_mul_f32 v[46:47], v[46:47], v[58:59] op_sel_hi:[1,0]
	v_pk_mul_f32 v[52:53], v[52:53], v[58:59] op_sel_hi:[1,0]
	v_pk_mul_f32 v[50:51], v[50:51], v[58:59] op_sel_hi:[1,0]
	v_pk_mul_f32 v[56:57], v[56:57], v[58:59] op_sel_hi:[1,0]
	v_pk_mul_f32 v[54:55], v[54:55], v[58:59] op_sel_hi:[1,0]
	v_cvt_pk_bf16_f32 v40, v40, v41
	v_cvt_pk_bf16_f32 v41, v44, v45
	v_cvt_pk_bf16_f32 v44, v46, v47
	v_cvt_pk_bf16_f32 v45, v48, v49
	v_cvt_pk_bf16_f32 v46, v50, v51
	v_cvt_pk_bf16_f32 v47, v52, v53
	v_cvt_pk_bf16_f32 v48, v54, v55
	v_cvt_pk_bf16_f32 v49, v56, v57
	global_store_dwordx2 v[60:61], v[40:41], off
	global_store_dwordx2 v[60:61], v[44:45], off offset:512
	global_store_dwordx2 v[60:61], v[46:47], off offset:1024
	global_store_dwordx2 v[60:61], v[48:49], off offset:1536
	s_andn2_b64 exec, exec, s[2:3]
	s_cbranch_execnz .Lrow2_top

; DI float bflo(unsigned u) { return __uint_as_float(u << 16); }
; DI float bfhi(unsigned u) { return __uint_as_float(u & 0xffff0000u); }
; DI int ltid() { int t = threadIdx.x; asm volatile("" : "+v"(t)); return t; }
; DI int lbid() { int b = blockIdx.x; asm volatile("" : "+s"(b)); return b; }
; DI void row_phase(const float* __restrict__ x_in, const u16* __restrict__ y, float c, const float* __restrict__ g_post,
;                   float* __restrict__ x_out, const float* __restrict__ g_pre, u16* __restrict__ hout) {
;   const int tid_ = ltid();
;   const int lane = tid_ & 63, wid = tid_ >> 6;
;   for (int row = lbid() * 8 + wid; row < S; row += gridDim.x * 8) {
;     f32x4 xv[4];
; #pragma unroll
;     for (int i = 0; i < 4; ++i) xv[i] = __builtin_nontemporal_load((const f32x4*)(x_in + (size_t)row * DM + 4 * lane + 256 * i));
;     if (y) {
;       f32x4 yv[4];
;       float ss = 0.f;
; #pragma unroll
;       for (int i = 0; i < 4; ++i) {
;         typedef unsigned u32x2_t __attribute__((ext_vector_type(2)));
;         const u32x2_t yb = __builtin_nontemporal_load((const u32x2_t*)(y + (size_t)row * DM + 4 * lane + 256 * i));
;         yv[i] = f32x4{bflo(yb.x), bfhi(yb.x), bflo(yb.y), bfhi(yb.y)};
;         ss += yv[i][0] * yv[i][0] + yv[i][1] * yv[i][1] + yv[i][2] * yv[i][2] + yv[i][3] * yv[i][3];
;       }
;       ss = wave_sum(ss);
;       float r = c * rsqrtf(ss * (1.f / DM) + EPS);
; #pragma unroll
;       for (int i = 0; i < 4; ++i) {
;         f32x4 g = *(const f32x4*)(g_post + 4 * lane + 256 * i);
;         xv[i] += yv[i] * g * r;
;         __builtin_nontemporal_store(xv[i], (f32x4*)(x_out + (size_t)row * DM + 4 * lane + 256 * i));
;       }
;     }
;     if (g_pre) {
;       float ss = 0.f;
; #pragma unroll
;       for (int i = 0; i < 4; ++i) ss += xv[i][0] * xv[i][0] + xv[i][1] * xv[i][1] + xv[i][2] * xv[i][2] + xv[i][3] * xv[i][3];
;       ss = wave_sum(ss);
;       float r = rsqrtf(ss * (1.f / DM) + EPS);
; #pragma unroll
;       for (int i = 0; i < 4; ++i) {
;         f32x4 g = *(const f32x4*)(g_pre + 4 * lane + 256 * i);
.LBB0_400:
	s_or_b64 exec, exec, s[0:1]
	v_mov_b32_e32 v0, v158
	s_mov_b32 s0, s92
	s_barrier
	s_nop 0
	v_ashrrev_i32_e32 v1, 6, v0
	v_lshl_add_u32 v32, s0, 3, v1
	s_movk_i32 s0, 0x4000
	v_cmp_gt_i32_e32 vcc, s0, v32
	s_and_saveexec_b64 s[0:1], vcc
	s_cbranch_execz .LBB0_403
	v_lshlrev_b32_e32 v0, 2, v0
	v_and_b32_e32 v33, 0xfc, v0
	v_lshlrev_b32_e32 v36, 2, v33
	v_mov_b32_e32 v37, 0
	v_lshl_add_u64 v[0:1], s[38:39], 0, v[36:37]
	s_mov_b64 s[2:3], 0x5000
	v_lshl_add_u64 v[34:35], v[0:1], 0, s[2:3]
	s_mov_b64 s[2:3], 0x6000
	v_lshl_add_u64 v[38:39], v[0:1], 0, s[2:3]
	s_movk_i32 s2, 0x6000
	v_add_co_u32_e32 v40, vcc, s2, v0
	s_lshl_b32 s4, s11, 3
	s_nop 0
	v_addc_co_u32_e32 v41, vcc, 0, v1, vcc
	global_load_dwordx4 v[0:3], v[34:35], off offset:1024
	global_load_dwordx4 v[4:7], v[34:35], off offset:2048
	global_load_dwordx4 v[8:11], v[40:41], off offset:-4096
	global_load_dwordx4 v[12:15], v[40:41], off
	global_load_dwordx4 v[16:19], v[34:35], off offset:3072
	global_load_dwordx4 v[20:23], v[38:39], off offset:1024
	global_load_dwordx4 v[24:27], v[38:39], off offset:2048
	global_load_dwordx4 v[28:31], v[38:39], off offset:3072
	v_lshlrev_b32_e32 v38, 1, v33
	v_mov_b32_e32 v39, v37
	v_lshl_add_u64 v[34:35], s[22:23], 0, v[36:37]
	v_lshl_add_u64 v[36:37], s[14:15], 0, v[38:39]
	v_lshl_add_u64 v[38:39], s[26:27], 0, v[38:39]
	s_mov_b64 s[2:3], 0
	v_mov_b32_e32 v42, 0x358637bd
	s_mov_b32 s5, 0x800000
	s_movk_i32 s6, 0x880
	s_movk_i32 s7, 0x3fff
	v_mov_b32_e32 v124, v32
	v_ashrrev_i32_e32 v125, 31, v32
	v_lshlrev_b64 v[126:127], 11, v[124:125]
	v_lshl_add_u64 v[126:127], v[36:37], 0, v[126:127]
	global_load_dwordx2 v[100:101], v[126:127], off offset:512 nt
	global_load_dwordx2 v[102:103], v[126:127], off nt
	global_load_dwordx2 v[104:105], v[126:127], off offset:1536 nt
	global_load_dwordx2 v[106:107], v[126:127], off offset:1024 nt
	v_lshlrev_b64 v[126:127], 12, v[124:125]
	v_lshl_add_u64 v[126:127], v[34:35], 0, v[126:127]
	global_load_dwordx4 v[108:111], v[126:127], off nt
	global_load_dwordx4 v[112:115], v[126:127], off offset:1024 nt
	global_load_dwordx4 v[116:119], v[126:127], off offset:2048 nt
	global_load_dwordx4 v[120:123], v[126:127], off offset:3072 nt
	s_waitcnt vmcnt(0)
	s_branch .Lrow3_aw

; DI float bflo(unsigned u) { return __uint_as_float(u << 16); }
; DI float bfhi(unsigned u) { return __uint_as_float(u & 0xffff0000u); }
; DI void row_phase(const float* __restrict__ x_in, const u16* __restrict__ y, float c, const float* __restrict__ g_post,
;                   float* __restrict__ x_out, const float* __restrict__ g_pre, u16* __restrict__ hout) {
;     ...
;         yv[i] = f32x4{bflo(yb.x), bfhi(yb.x), bflo(yb.y), bfhi(yb.y)};
;         ss += yv[i][0] * yv[i][0] + yv[i][1] * yv[i][1] + yv[i][2] * yv[i][2] + yv[i][3] * yv[i][3];
;       }
;       ss = wave_sum(ss);
;       float r = c * rsqrtf(ss * (1.f / DM) + EPS);
; #pragma unroll
;       for (int i = 0; i < 4; ++i) {
;         f32x4 g = *(const f32x4*)(g_post + 4 * lane + 256 * i);
;         xv[i] += yv[i] * g * r;
;         __builtin_nontemporal_store(xv[i], (f32x4*)(x_out + (size_t)row * DM + 4 * lane + 256 * i));
;       }
;     }
;     if (g_pre) {
;       float ss = 0.f;
; #pragma unroll
;       for (int i = 0; i < 4; ++i) ss += xv[i][0] * xv[i][0] + xv[i][1] * xv[i][1] + xv[i][2] * xv[i][2] + xv[i][3] * xv[i][3];
;       ss = wave_sum(ss);
;       float r = rsqrtf(ss * (1.f / DM) + EPS);
; #pragma unroll
;       for (int i = 0; i < 4; ++i) {
;         f32x4 g = *(const f32x4*)(g_pre + 4 * lane + 256 * i);
;         f32x4 hv = xv[i] * g * r;
;         uint2 o = {pack2(hv[0], hv[1]), pack2(hv[2], hv[3])};
;         *(uint2*)(hout + (size_t)row * LDH + 4 * lane + 256 * i) = o;
;       }
.Lrow3_nopf:
	s_or_b64 exec, exec, s[98:99]
	v_and_b32_e32 v71, 0xffff0000, v60
	v_and_b32_e32 v70, 0xffff0000, v62
	v_lshlrev_b32_e32 v69, 16, v60
	v_lshlrev_b32_e32 v68, 16, v62
	v_lshlrev_b32_e32 v72, 16, v63
	v_and_b32_e32 v60, 0xffff0000, v63
	v_lshlrev_b32_e32 v63, 16, v64
	v_lshlrev_b32_e32 v62, 16, v66
	v_and_b32_e32 v75, 0xffff0000, v64
	v_and_b32_e32 v74, 0xffff0000, v66
	v_lshlrev_b32_e32 v76, 16, v67
	v_and_b32_e32 v64, 0xffff0000, v67
	v_pk_mul_f32 v[66:67], v[70:71], v[70:71]
	v_lshlrev_b32_e32 v73, 16, v61
	v_pk_mul_f32 v[78:79], v[74:75], v[74:75]
	v_pk_fma_f32 v[66:67], v[68:69], v[68:69], v[66:67]
	v_and_b32_e32 v61, 0xffff0000, v61
	v_lshlrev_b32_e32 v77, 16, v65
	v_pk_fma_f32 v[78:79], v[62:63], v[62:63], v[78:79]
	v_pk_fma_f32 v[66:67], v[72:73], v[72:73], v[66:67]
	v_and_b32_e32 v65, 0xffff0000, v65
	v_pk_fma_f32 v[78:79], v[76:77], v[76:77], v[78:79]
	v_pk_fma_f32 v[66:67], v[60:61], v[60:61], v[66:67]
	v_pk_fma_f32 v[78:79], v[64:65], v[64:65], v[78:79]
	v_add_f32_e32 v33, v66, v67
	v_add_f32_e32 v33, v33, v78
	v_add_f32_e32 v33, v33, v79
	ds_bpermute_b32 v43, v159, v33
	v_mov_b32_e32 v66, v68
	v_mov_b32_e32 v67, v70
	v_mov_b32_e32 v70, v69
	v_mov_b32_e32 v78, v72
	s_waitcnt lgkmcnt(0)
	v_add_f32_e32 v33, v33, v43
	ds_bpermute_b32 v43, v160, v33
	v_mov_b32_e32 v68, v62
	v_mov_b32_e32 v69, v74
	v_mov_b32_e32 v74, v63
	v_pk_mul_f32 v[62:63], v[8:9], v[66:67]
	s_waitcnt lgkmcnt(0)
	v_add_f32_e32 v33, v33, v43
	ds_bpermute_b32 v43, v161, v33
	v_pk_mul_f32 v[70:71], v[0:1], v[70:71]
	v_mov_b32_e32 v79, v60
	v_pk_mul_f32 v[68:69], v[4:5], v[68:69]
	v_pk_mul_f32 v[74:75], v[16:17], v[74:75]
	s_waitcnt lgkmcnt(0)
	v_add_f32_e32 v33, v33, v43
	ds_bpermute_b32 v43, v162, v33
	v_mov_b32_e32 v60, v73
	v_mov_b32_e32 v80, v76
	v_mov_b32_e32 v81, v64
	v_pk_mul_f32 v[66:67], v[10:11], v[78:79]
	s_waitcnt lgkmcnt(0)
	v_add_f32_e32 v33, v33, v43
	ds_bpermute_b32 v43, v163, v33
	v_mov_b32_e32 v64, v77
	v_pk_mul_f32 v[60:61], v[2:3], v[60:61]
	v_pk_mul_f32 v[78:79], v[6:7], v[80:81]
	v_pk_mul_f32 v[64:65], v[18:19], v[64:65]
	s_waitcnt lgkmcnt(0)
	v_add_f32_e32 v33, v33, v43
	ds_bpermute_b32 v43, v164, v33
	s_waitcnt lgkmcnt(0)
	v_add_f32_e32 v33, v33, v43
	v_fmamk_f32 v33, v33, 0x3a800000, v42
	v_mul_f32_e32 v43, 0x4b800000, v33
	v_cmp_gt_f32_e32 vcc, s5, v33
	s_nop 1
	v_cndmask_b32_e32 v33, v33, v43, vcc
	v_rsq_f32_e32 v33, v33
	s_nop 0
	v_mul_f32_e32 v43, 0x45800000, v33
	v_cndmask_b32_e32 v33, v33, v43, vcc
	v_mul_f32_e32 v72, 0.5, v33
	v_pk_fma_f32 v[44:45], v[62:63], v[72:73], v[44:45] op_sel_hi:[1,0,1]
	v_pk_fma_f32 v[48:49], v[70:71], v[72:73], v[48:49] op_sel_hi:[1,0,1]
	v_pk_fma_f32 v[52:53], v[68:69], v[72:73], v[52:53] op_sel_hi:[1,0,1]
	v_pk_fma_f32 v[56:57], v[74:75], v[72:73], v[56:57] op_sel_hi:[1,0,1]
	v_mov_b32_e32 v62, v45
	v_mov_b32_e32 v63, v49
	v_pk_fma_f32 v[46:47], v[66:67], v[72:73], v[46:47] op_sel_hi:[1,0,1]
	v_pk_fma_f32 v[50:51], v[60:61], v[72:73], v[50:51] op_sel_hi:[1,0,1]
	v_mov_b32_e32 v60, v44
	v_mov_b32_e32 v61, v48
	v_mov_b32_e32 v70, v57
	v_mov_b32_e32 v71, v53
	v_pk_mul_f32 v[62:63], v[62:63], v[62:63]
	v_pk_fma_f32 v[54:55], v[78:79], v[72:73], v[54:55] op_sel_hi:[1,0,1]
	v_pk_fma_f32 v[58:59], v[64:65], v[72:73], v[58:59] op_sel_hi:[1,0,1]
	v_mov_b32_e32 v64, v46
	v_mov_b32_e32 v65, v50
	v_mov_b32_e32 v68, v56
	v_mov_b32_e32 v69, v52
	v_pk_mul_f32 v[70:71], v[70:71], v[70:71]
	v_pk_fma_f32 v[60:61], v[60:61], v[60:61], v[62:63]
	v_mov_b32_e32 v66, v47
	v_mov_b32_e32 v67, v51
	v_mov_b32_e32 v72, v58
	v_mov_b32_e32 v73, v54
	v_pk_fma_f32 v[62:63], v[68:69], v[68:69], v[70:71]
	v_pk_fma_f32 v[60:61], v[64:65], v[64:65], v[60:61]
	v_mov_b32_e32 v74, v59
	v_mov_b32_e32 v75, v55
	v_pk_fma_f32 v[62:63], v[72:73], v[72:73], v[62:63]
	v_pk_fma_f32 v[60:61], v[66:67], v[66:67], v[60:61]
	v_pk_fma_f32 v[62:63], v[74:75], v[74:75], v[62:63]
	v_add_f32_e32 v33, v60, v61
	v_add_f32_e32 v33, v63, v33
	v_add_f32_e32 v33, v62, v33
	ds_bpermute_b32 v43, v159, v33
	v_mad_i64_i32 v[60:61], s[34:35], v32, s6, v[38:39]
	v_add_u32_e32 v32, s4, v32
	v_cmp_lt_i32_e32 vcc, s7, v32
	s_waitcnt lgkmcnt(0)
	v_add_f32_e32 v33, v33, v43
	ds_bpermute_b32 v43, v160, v33
	s_or_b64 s[2:3], vcc, s[2:3]
	global_store_dwordx4 v[40:41], v[44:47], off nt
	global_store_dwordx4 v[40:41], v[48:51], off offset:1024 nt
	global_store_dwordx4 v[40:41], v[52:55], off offset:2048 nt
	global_store_dwordx4 v[40:41], v[56:59], off offset:3072 nt
	v_pk_mul_f32 v[40:41], v[12:13], v[44:45]
	s_waitcnt lgkmcnt(0)
	v_add_f32_e32 v33, v33, v43
	ds_bpermute_b32 v43, v161, v33
	v_pk_mul_f32 v[44:45], v[14:15], v[46:47]
	v_pk_mul_f32 v[46:47], v[20:21], v[48:49]
	v_pk_mul_f32 v[48:49], v[22:23], v[50:51]
	v_pk_mul_f32 v[50:51], v[24:25], v[52:53]
	s_waitcnt lgkmcnt(0)
	v_add_f32_e32 v33, v33, v43
	ds_bpermute_b32 v43, v162, v33
	v_pk_mul_f32 v[52:53], v[26:27], v[54:55]
	v_pk_mul_f32 v[54:55], v[28:29], v[56:57]
	v_pk_mul_f32 v[56:57], v[30:31], v[58:59]
	s_waitcnt lgkmcnt(0)
	v_add_f32_e32 v33, v33, v43
	ds_bpermute_b32 v43, v163, v33
	s_waitcnt lgkmcnt(0)
	v_add_f32_e32 v33, v33, v43
	ds_bpermute_b32 v43, v164, v33
	s_waitcnt lgkmcnt(0)
	v_add_f32_e32 v33, v33, v43
	v_fmamk_f32 v33, v33, 0x3a800000, v42
	v_mul_f32_e32 v43, 0x4b800000, v33
	v_cmp_gt_f32_e32 vcc, s5, v33
	s_nop 1
	v_cndmask_b32_e32 v33, v33, v43, vcc
	v_rsq_f32_e32 v33, v33
	s_nop 0
	v_mul_f32_e32 v43, 0x45800000, v33
	v_cndmask_b32_e32 v58, v33, v43, vcc
	v_pk_mul_f32 v[44:45], v[44:45], v[58:59] op_sel_hi:[1,0]
	v_pk_mul_f32 v[40:41], v[40:41], v[58:59] op_sel_hi:[1,0]
	v_pk_mul_f32 v[48:49], v[48:49], v[58:59] op_sel_hi:[1,0]
	v_pk_mul_f32 v[46:47], v[46:47], v[58:59] op_sel_hi:[1,0]
	v_pk_mul_f32 v[52:53], v[52:53], v[58:59] op_sel_hi:[1,0]
	v_pk_mul_f32 v[50:51], v[50:51], v[58:59] op_sel_hi:[1,0]
	v_pk_mul_f32 v[56:57], v[56:57], v[58:59] op_sel_hi:[1,0]
	v_pk_mul_f32 v[54:55], v[54:55], v[58:59] op_sel_hi:[1,0]
	v_cvt_pk_bf16_f32 v40, v40, v41
	v_cvt_pk_bf16_f32 v41, v44, v45
	v_cvt_pk_bf16_f32 v44, v46, v47
	v_cvt_pk_bf16_f32 v45, v48, v49
	v_cvt_pk_bf16_f32 v46, v50, v51
	v_cvt_pk_bf16_f32 v47, v52, v53
	v_cvt_pk_bf16_f32 v48, v54, v55
	v_cvt_pk_bf16_f32 v49, v56, v57
	global_store_dwordx2 v[60:61], v[40:41], off
	global_store_dwordx2 v[60:61], v[44:45], off offset:512
	global_store_dwordx2 v[60:61], v[46:47], off offset:1024
	global_store_dwordx2 v[60:61], v[48:49], off offset:1536
	s_andn2_b64 exec, exec, s[2:3]
	s_cbranch_execnz .Lrow3_top

; DI float bflo(unsigned u) { return __uint_as_float(u << 16); }
; DI float bfhi(unsigned u) { return __uint_as_float(u & 0xffff0000u); }
; DI int ltid() { int t = threadIdx.x; asm volatile("" : "+v"(t)); return t; }
; DI int lbid() { int b = blockIdx.x; asm volatile("" : "+s"(b)); return b; }
; DI void row_phase(const float* __restrict__ x_in, const u16* __restrict__ y, float c, const float* __restrict__ g_post,
;                   float* __restrict__ x_out, const float* __restrict__ g_pre, u16* __restrict__ hout) {
;   const int tid_ = ltid();
;   const int lane = tid_ & 63, wid = tid_ >> 6;
;   for (int row = lbid() * 8 + wid; row < S; row += gridDim.x * 8) {
;     f32x4 xv[4];
; #pragma unroll
;     for (int i = 0; i < 4; ++i) xv[i] = __builtin_nontemporal_load((const f32x4*)(x_in + (size_t)row * DM + 4 * lane + 256 * i));
;     if (y) {
;       f32x4 yv[4];
;       float ss = 0.f;
; #pragma unroll
;       for (int i = 0; i < 4; ++i) {
;         typedef unsigned u32x2_t __attribute__((ext_vector_type(2)));
;         const u32x2_t yb = __builtin_nontemporal_load((const u32x2_t*)(y + (size_t)row * DM + 4 * lane + 256 * i));
;         yv[i] = f32x4{bflo(yb.x), bfhi(yb.x), bflo(yb.y), bfhi(yb.y)};
;         ss += yv[i][0] * yv[i][0] + yv[i][1] * yv[i][1] + yv[i][2] * yv[i][2] + yv[i][3] * yv[i][3];
;       }
;       ss = wave_sum(ss);
;       float r = c * rsqrtf(ss * (1.f / DM) + EPS);
; #pragma unroll
;       for (int i = 0; i < 4; ++i) {
;         f32x4 g = *(const f32x4*)(g_post + 4 * lane + 256 * i);
;         xv[i] += yv[i] * g * r;
;         __builtin_nontemporal_store(xv[i], (f32x4*)(x_out + (size_t)row * DM + 4 * lane + 256 * i));
;       }
;     }
;     if (g_pre) {
;       float ss = 0.f;
; #pragma unroll
;       for (int i = 0; i < 4; ++i) ss += xv[i][0] * xv[i][0] + xv[i][1] * xv[i][1] + xv[i][2] * xv[i][2] + xv[i][3] * xv[i][3];
;       ss = wave_sum(ss);
;       float r = rsqrtf(ss * (1.f / DM) + EPS);
; #pragma unroll
;       for (int i = 0; i < 4; ++i) {
;         f32x4 g = *(const f32x4*)(g_pre + 4 * lane + 256 * i);
.LBB0_488:
	s_or_b64 exec, exec, s[0:1]
	v_mov_b32_e32 v0, v158
	s_mov_b32 s0, s92
	s_barrier
	s_nop 0
	v_ashrrev_i32_e32 v1, 6, v0
	v_lshl_add_u32 v32, s0, 3, v1
	s_movk_i32 s0, 0x4000
	v_cmp_gt_i32_e32 vcc, s0, v32
	s_and_saveexec_b64 s[0:1], vcc
	s_cbranch_execz .LBB0_491
	v_lshlrev_b32_e32 v0, 2, v0
	v_and_b32_e32 v33, 0xfc, v0
	v_lshlrev_b32_e32 v36, 2, v33
	v_mov_b32_e32 v37, 0
	v_lshl_add_u64 v[0:1], s[38:39], 0, v[36:37]
	s_mov_b64 s[2:3], 0x7000
	v_lshl_add_u64 v[34:35], v[0:1], 0, s[2:3]
	s_mov_b64 s[2:3], 0x8000
	v_lshl_add_u64 v[38:39], v[0:1], 0, s[2:3]
	s_mov_b32 s2, 0x8000
	v_add_co_u32_e32 v40, vcc, s2, v0
	s_lshl_b32 s4, s11, 3
	s_nop 0
	v_addc_co_u32_e32 v41, vcc, 0, v1, vcc
	global_load_dwordx4 v[0:3], v[34:35], off offset:1024
	global_load_dwordx4 v[4:7], v[34:35], off offset:2048
	global_load_dwordx4 v[8:11], v[40:41], off offset:-4096
	global_load_dwordx4 v[12:15], v[40:41], off
	global_load_dwordx4 v[16:19], v[34:35], off offset:3072
	global_load_dwordx4 v[20:23], v[38:39], off offset:1024
	global_load_dwordx4 v[24:27], v[38:39], off offset:2048
	global_load_dwordx4 v[28:31], v[38:39], off offset:3072
	v_lshlrev_b32_e32 v38, 1, v33
	v_mov_b32_e32 v39, v37
	v_lshl_add_u64 v[34:35], s[22:23], 0, v[36:37]
	v_lshl_add_u64 v[36:37], s[14:15], 0, v[38:39]
	v_lshl_add_u64 v[38:39], s[26:27], 0, v[38:39]
	s_mov_b64 s[2:3], 0
	v_mov_b32_e32 v42, 0x358637bd
	s_mov_b32 s5, 0x800000
	s_movk_i32 s6, 0x880
	s_movk_i32 s7, 0x3fff
	v_mov_b32_e32 v124, v32
	v_ashrrev_i32_e32 v125, 31, v32
	v_lshlrev_b64 v[126:127], 11, v[124:125]
	v_lshl_add_u64 v[126:127], v[36:37], 0, v[126:127]
	global_load_dwordx2 v[100:101], v[126:127], off offset:512 nt
	global_load_dwordx2 v[102:103], v[126:127], off nt
	global_load_dwordx2 v[104:105], v[126:127], off offset:1536 nt
	global_load_dwordx2 v[106:107], v[126:127], off offset:1024 nt
	v_lshlrev_b64 v[126:127], 12, v[124:125]
	v_lshl_add_u64 v[126:127], v[34:35], 0, v[126:127]
	global_load_dwordx4 v[108:111], v[126:127], off nt
	global_load_dwordx4 v[112:115], v[126:127], off offset:1024 nt
	global_load_dwordx4 v[116:119], v[126:127], off offset:2048 nt
	global_load_dwordx4 v[120:123], v[126:127], off offset:3072 nt
	s_waitcnt vmcnt(0)
	s_branch .Lrow4_aw

; DI float bflo(unsigned u) { return __uint_as_float(u << 16); }
; DI float bfhi(unsigned u) { return __uint_as_float(u & 0xffff0000u); }
; DI int ltid() { int t = threadIdx.x; asm volatile("" : "+v"(t)); return t; }
; DI int lbid() { int b = blockIdx.x; asm volatile("" : "+s"(b)); return b; }
; DI void row_phase(const float* __restrict__ x_in, const u16* __restrict__ y, float c, const float* __restrict__ g_post,
;                   float* __restrict__ x_out, const float* __restrict__ g_pre, u16* __restrict__ hout) {
;   const int tid_ = ltid();
;   const int lane = tid_ & 63, wid = tid_ >> 6;
;   for (int row = lbid() * 8 + wid; row < S; row += gridDim.x * 8) {
;     f32x4 xv[4];
; #pragma unroll
;     for (int i = 0; i < 4; ++i) xv[i] = __builtin_nontemporal_load((const f32x4*)(x_in + (size_t)row * DM + 4 * lane + 256 * i));
;     if (y) {
;       f32x4 yv[4];
;       float ss = 0.f;
; #pragma unroll
;       for (int i = 0; i < 4; ++i) {
;         typedef unsigned u32x2_t __attribute__((ext_vector_type(2)));
;         const u32x2_t yb = __builtin_nontemporal_load((const u32x2_t*)(y + (size_t)row * DM + 4 * lane + 256 * i));
;         yv[i] = f32x4{bflo(yb.x), bfhi(yb.x), bflo(yb.y), bfhi(yb.y)};
;         ss += yv[i][0] * yv[i][0] + yv[i][1] * yv[i][1] + yv[i][2] * yv[i][2] + yv[i][3] * yv[i][3];
;       }
;       ss = wave_sum(ss);
;       float r = c * rsqrtf(ss * (1.f / DM) + EPS);
; #pragma unroll
;       for (int i = 0; i < 4; ++i) {
;         f32x4 g = *(const f32x4*)(g_post + 4 * lane + 256 * i);
;         xv[i] += yv[i] * g * r;
;         __builtin_nontemporal_store(xv[i], (f32x4*)(x_out + (size_t)row * DM + 4 * lane + 256 * i));
;       }
;     }
;     if (g_pre) {
;       float ss = 0.f;
; #pragma unroll
;       for (int i = 0; i < 4; ++i) ss += xv[i][0] * xv[i][0] + xv[i][1] * xv[i][1] + xv[i][2] * xv[i][2] + xv[i][3] * xv[i][3];
;       ss = wave_sum(ss);
;       float r = rsqrtf(ss * (1.f / DM) + EPS);
; #pragma unroll
;       for (int i = 0; i < 4; ++i) {
;         f32x4 g = *(const f32x4*)(g_pre + 4 * lane + 256 * i);
.LBB0_703:
	s_or_b64 exec, exec, s[0:1]
	v_mov_b32_e32 v0, v158
	s_mov_b32 s0, s92
	s_barrier
	s_nop 0
	v_ashrrev_i32_e32 v1, 6, v0
	v_lshl_add_u32 v32, s0, 3, v1
	s_movk_i32 s0, 0x4000
	v_cmp_gt_i32_e32 vcc, s0, v32
	s_and_saveexec_b64 s[0:1], vcc
	s_cbranch_execz .LBB0_706
	v_lshlrev_b32_e32 v0, 2, v0
	v_and_b32_e32 v33, 0xfc, v0
	v_lshlrev_b32_e32 v36, 2, v33
	v_mov_b32_e32 v37, 0
	v_lshl_add_u64 v[0:1], s[38:39], 0, v[36:37]
	s_mov_b64 s[2:3], 0x9000
	v_lshl_add_u64 v[34:35], v[0:1], 0, s[2:3]
	s_mov_b64 s[2:3], 0xa000
	v_lshl_add_u64 v[38:39], v[0:1], 0, s[2:3]
	s_mov_b32 s2, 0xa000
	v_add_co_u32_e32 v40, vcc, s2, v0
	s_lshl_b32 s4, s11, 3
	s_nop 0
	v_addc_co_u32_e32 v41, vcc, 0, v1, vcc
	global_load_dwordx4 v[0:3], v[34:35], off offset:1024
	global_load_dwordx4 v[4:7], v[34:35], off offset:2048
	global_load_dwordx4 v[8:11], v[40:41], off offset:-4096
	global_load_dwordx4 v[12:15], v[40:41], off
	global_load_dwordx4 v[16:19], v[34:35], off offset:3072
	global_load_dwordx4 v[20:23], v[38:39], off offset:1024
	global_load_dwordx4 v[24:27], v[38:39], off offset:2048
	global_load_dwordx4 v[28:31], v[38:39], off offset:3072
	v_lshlrev_b32_e32 v38, 1, v33
	v_mov_b32_e32 v39, v37
	v_lshl_add_u64 v[34:35], s[22:23], 0, v[36:37]
	v_lshl_add_u64 v[36:37], s[14:15], 0, v[38:39]
	v_lshl_add_u64 v[38:39], s[26:27], 0, v[38:39]
	s_mov_b64 s[2:3], 0
	v_mov_b32_e32 v42, 0x358637bd
	s_mov_b32 s5, 0x800000
	s_movk_i32 s6, 0x880
	s_movk_i32 s7, 0x3fff
	v_mov_b32_e32 v124, v32
	v_ashrrev_i32_e32 v125, 31, v32
	v_lshlrev_b64 v[126:127], 11, v[124:125]
	v_lshl_add_u64 v[126:127], v[36:37], 0, v[126:127]
	global_load_dwordx2 v[100:101], v[126:127], off offset:512 nt
	global_load_dwordx2 v[102:103], v[126:127], off nt
	global_load_dwordx2 v[104:105], v[126:127], off offset:1536 nt
	global_load_dwordx2 v[106:107], v[126:127], off offset:1024 nt
	v_lshlrev_b64 v[126:127], 12, v[124:125]
	v_lshl_add_u64 v[126:127], v[34:35], 0, v[126:127]
	global_load_dwordx4 v[108:111], v[126:127], off nt
	global_load_dwordx4 v[112:115], v[126:127], off offset:1024 nt
	global_load_dwordx4 v[116:119], v[126:127], off offset:2048 nt
	global_load_dwordx4 v[120:123], v[126:127], off offset:3072 nt
	s_waitcnt vmcnt(0)
	s_branch .Lrow5_aw

; DI float bflo(unsigned u) { return __uint_as_float(u << 16); }
; DI float bfhi(unsigned u) { return __uint_as_float(u & 0xffff0000u); }
; DI void row_phase(const float* __restrict__ x_in, const u16* __restrict__ y, float c, const float* __restrict__ g_post,
;                   float* __restrict__ x_out, const float* __restrict__ g_pre, u16* __restrict__ hout) {
;     ...
;         yv[i] = f32x4{bflo(yb.x), bfhi(yb.x), bflo(yb.y), bfhi(yb.y)};
;         ss += yv[i][0] * yv[i][0] + yv[i][1] * yv[i][1] + yv[i][2] * yv[i][2] + yv[i][3] * yv[i][3];
;       }
;       ss = wave_sum(ss);
;       float r = c * rsqrtf(ss * (1.f / DM) + EPS);
; #pragma unroll
;       for (int i = 0; i < 4; ++i) {
;         f32x4 g = *(const f32x4*)(g_post + 4 * lane + 256 * i);
;         xv[i] += yv[i] * g * r;
;         __builtin_nontemporal_store(xv[i], (f32x4*)(x_out + (size_t)row * DM + 4 * lane + 256 * i));
;       }
;     }
;     if (g_pre) {
;       float ss = 0.f;
; #pragma unroll
;       for (int i = 0; i < 4; ++i) ss += xv[i][0] * xv[i][0] + xv[i][1] * xv[i][1] + xv[i][2] * xv[i][2] + xv[i][3] * xv[i][3];
;       ss = wave_sum(ss);
;       float r = rsqrtf(ss * (1.f / DM) + EPS);
; #pragma unroll
;       for (int i = 0; i < 4; ++i) {
;         f32x4 g = *(const f32x4*)(g_pre + 4 * lane + 256 * i);
;         f32x4 hv = xv[i] * g * r;
;         uint2 o = {pack2(hv[0], hv[1]), pack2(hv[2], hv[3])};
;         *(uint2*)(hout + (size_t)row * LDH + 4 * lane + 256 * i) = o;
;       }
.Lrow5_nopf:
	s_or_b64 exec, exec, s[98:99]
	v_and_b32_e32 v71, 0xffff0000, v60
	v_and_b32_e32 v70, 0xffff0000, v62
	v_lshlrev_b32_e32 v69, 16, v60
	v_lshlrev_b32_e32 v68, 16, v62
	v_lshlrev_b32_e32 v72, 16, v63
	v_and_b32_e32 v60, 0xffff0000, v63
	v_lshlrev_b32_e32 v63, 16, v64
	v_lshlrev_b32_e32 v62, 16, v66
	v_and_b32_e32 v75, 0xffff0000, v64
	v_and_b32_e32 v74, 0xffff0000, v66
	v_lshlrev_b32_e32 v76, 16, v67
	v_and_b32_e32 v64, 0xffff0000, v67
	v_pk_mul_f32 v[66:67], v[70:71], v[70:71]
	v_lshlrev_b32_e32 v73, 16, v61
	v_pk_mul_f32 v[78:79], v[74:75], v[74:75]
	v_pk_fma_f32 v[66:67], v[68:69], v[68:69], v[66:67]
	v_and_b32_e32 v61, 0xffff0000, v61
	v_lshlrev_b32_e32 v77, 16, v65
	v_pk_fma_f32 v[78:79], v[62:63], v[62:63], v[78:79]
	v_pk_fma_f32 v[66:67], v[72:73], v[72:73], v[66:67]
	v_and_b32_e32 v65, 0xffff0000, v65
	v_pk_fma_f32 v[78:79], v[76:77], v[76:77], v[78:79]
	v_pk_fma_f32 v[66:67], v[60:61], v[60:61], v[66:67]
	v_pk_fma_f32 v[78:79], v[64:65], v[64:65], v[78:79]
	v_add_f32_e32 v33, v66, v67
	v_add_f32_e32 v33, v33, v78
	v_add_f32_e32 v33, v33, v79
	ds_bpermute_b32 v43, v159, v33
	v_mov_b32_e32 v66, v68
	v_mov_b32_e32 v67, v70
	v_mov_b32_e32 v70, v69
	v_mov_b32_e32 v78, v72
	s_waitcnt lgkmcnt(0)
	v_add_f32_e32 v33, v33, v43
	ds_bpermute_b32 v43, v160, v33
	v_mov_b32_e32 v68, v62
	v_mov_b32_e32 v69, v74
	v_mov_b32_e32 v74, v63
	v_pk_mul_f32 v[62:63], v[8:9], v[66:67]
	s_waitcnt lgkmcnt(0)
	v_add_f32_e32 v33, v33, v43
	ds_bpermute_b32 v43, v161, v33
	v_pk_mul_f32 v[70:71], v[0:1], v[70:71]
	v_mov_b32_e32 v79, v60
	v_pk_mul_f32 v[68:69], v[4:5], v[68:69]
	v_pk_mul_f32 v[74:75], v[16:17], v[74:75]
	s_waitcnt lgkmcnt(0)
	v_add_f32_e32 v33, v33, v43
	ds_bpermute_b32 v43, v162, v33
	v_mov_b32_e32 v60, v73
	v_mov_b32_e32 v80, v76
	v_mov_b32_e32 v81, v64
	v_pk_mul_f32 v[66:67], v[10:11], v[78:79]
	s_waitcnt lgkmcnt(0)
	v_add_f32_e32 v33, v33, v43
	ds_bpermute_b32 v43, v163, v33
	v_mov_b32_e32 v64, v77
	v_pk_mul_f32 v[60:61], v[2:3], v[60:61]
	v_pk_mul_f32 v[78:79], v[6:7], v[80:81]
	v_pk_mul_f32 v[64:65], v[18:19], v[64:65]
	s_waitcnt lgkmcnt(0)
	v_add_f32_e32 v33, v33, v43
	ds_bpermute_b32 v43, v164, v33
	s_waitcnt lgkmcnt(0)
	v_add_f32_e32 v33, v33, v43
	v_fmamk_f32 v33, v33, 0x3a800000, v42
	v_mul_f32_e32 v43, 0x4b800000, v33
	v_cmp_gt_f32_e32 vcc, s5, v33
	s_nop 1
	v_cndmask_b32_e32 v33, v33, v43, vcc
	v_rsq_f32_e32 v33, v33
	s_nop 0
	v_mul_f32_e32 v43, 0x45800000, v33
	v_cndmask_b32_e32 v72, v33, v43, vcc
	v_pk_fma_f32 v[44:45], v[62:63], v[72:73], v[44:45] op_sel_hi:[1,0,1]
	v_pk_fma_f32 v[48:49], v[70:71], v[72:73], v[48:49] op_sel_hi:[1,0,1]
	v_pk_fma_f32 v[52:53], v[68:69], v[72:73], v[52:53] op_sel_hi:[1,0,1]
	v_pk_fma_f32 v[56:57], v[74:75], v[72:73], v[56:57] op_sel_hi:[1,0,1]
	v_mov_b32_e32 v62, v45
	v_mov_b32_e32 v63, v49
	v_pk_fma_f32 v[46:47], v[66:67], v[72:73], v[46:47] op_sel_hi:[1,0,1]
	v_pk_fma_f32 v[50:51], v[60:61], v[72:73], v[50:51] op_sel_hi:[1,0,1]
	v_mov_b32_e32 v60, v44
	v_mov_b32_e32 v61, v48
	v_mov_b32_e32 v70, v57
	v_mov_b32_e32 v71, v53
	v_pk_mul_f32 v[62:63], v[62:63], v[62:63]
	v_pk_fma_f32 v[54:55], v[78:79], v[72:73], v[54:55] op_sel_hi:[1,0,1]
	v_pk_fma_f32 v[58:59], v[64:65], v[72:73], v[58:59] op_sel_hi:[1,0,1]
	v_mov_b32_e32 v64, v46
	v_mov_b32_e32 v65, v50
	v_mov_b32_e32 v68, v56
	v_mov_b32_e32 v69, v52
	v_pk_mul_f32 v[70:71], v[70:71], v[70:71]
	v_pk_fma_f32 v[60:61], v[60:61], v[60:61], v[62:63]
	v_mov_b32_e32 v66, v47
	v_mov_b32_e32 v67, v51
	v_mov_b32_e32 v72, v58
	v_mov_b32_e32 v73, v54
	v_pk_fma_f32 v[62:63], v[68:69], v[68:69], v[70:71]
	v_pk_fma_f32 v[60:61], v[64:65], v[64:65], v[60:61]
	v_mov_b32_e32 v74, v59
	v_mov_b32_e32 v75, v55
	v_pk_fma_f32 v[62:63], v[72:73], v[72:73], v[62:63]
	v_pk_fma_f32 v[60:61], v[66:67], v[66:67], v[60:61]
	v_pk_fma_f32 v[62:63], v[74:75], v[74:75], v[62:63]
	v_add_f32_e32 v33, v60, v61
	v_add_f32_e32 v33, v63, v33
	v_add_f32_e32 v33, v62, v33
	ds_bpermute_b32 v43, v159, v33
	v_mad_i64_i32 v[60:61], s[16:17], v32, s6, v[38:39]
	v_add_u32_e32 v32, s4, v32
	v_cmp_lt_i32_e32 vcc, s7, v32
	s_waitcnt lgkmcnt(0)
	v_add_f32_e32 v33, v33, v43
	ds_bpermute_b32 v43, v160, v33
	s_or_b64 s[2:3], vcc, s[2:3]
	global_store_dwordx4 v[40:41], v[44:47], off nt
	global_store_dwordx4 v[40:41], v[48:51], off offset:1024 nt
	global_store_dwordx4 v[40:41], v[52:55], off offset:2048 nt
	global_store_dwordx4 v[40:41], v[56:59], off offset:3072 nt
	v_pk_mul_f32 v[40:41], v[12:13], v[44:45]
	s_waitcnt lgkmcnt(0)
	v_add_f32_e32 v33, v33, v43
	ds_bpermute_b32 v43, v161, v33
	v_pk_mul_f32 v[44:45], v[14:15], v[46:47]
	v_pk_mul_f32 v[46:47], v[20:21], v[48:49]
	v_pk_mul_f32 v[48:49], v[22:23], v[50:51]
	v_pk_mul_f32 v[50:51], v[24:25], v[52:53]
	s_waitcnt lgkmcnt(0)
	v_add_f32_e32 v33, v33, v43
	ds_bpermute_b32 v43, v162, v33
	v_pk_mul_f32 v[52:53], v[26:27], v[54:55]
	v_pk_mul_f32 v[54:55], v[28:29], v[56:57]
	v_pk_mul_f32 v[56:57], v[30:31], v[58:59]
	s_waitcnt lgkmcnt(0)
	v_add_f32_e32 v33, v33, v43
	ds_bpermute_b32 v43, v163, v33
	s_waitcnt lgkmcnt(0)
	v_add_f32_e32 v33, v33, v43
	ds_bpermute_b32 v43, v164, v33
	s_waitcnt lgkmcnt(0)
	v_add_f32_e32 v33, v33, v43
	v_fmamk_f32 v33, v33, 0x3a800000, v42
	v_mul_f32_e32 v43, 0x4b800000, v33
	v_cmp_gt_f32_e32 vcc, s5, v33
	s_nop 1
	v_cndmask_b32_e32 v33, v33, v43, vcc
	v_rsq_f32_e32 v33, v33
	s_nop 0
	v_mul_f32_e32 v43, 0x45800000, v33
	v_cndmask_b32_e32 v58, v33, v43, vcc
	v_pk_mul_f32 v[44:45], v[44:45], v[58:59] op_sel_hi:[1,0]
	v_pk_mul_f32 v[40:41], v[40:41], v[58:59] op_sel_hi:[1,0]
	v_pk_mul_f32 v[48:49], v[48:49], v[58:59] op_sel_hi:[1,0]
	v_pk_mul_f32 v[46:47], v[46:47], v[58:59] op_sel_hi:[1,0]
	v_pk_mul_f32 v[52:53], v[52:53], v[58:59] op_sel_hi:[1,0]
	v_pk_mul_f32 v[50:51], v[50:51], v[58:59] op_sel_hi:[1,0]
	v_pk_mul_f32 v[56:57], v[56:57], v[58:59] op_sel_hi:[1,0]
	v_pk_mul_f32 v[54:55], v[54:55], v[58:59] op_sel_hi:[1,0]
	v_cvt_pk_bf16_f32 v40, v40, v41
	v_cvt_pk_bf16_f32 v41, v44, v45
	v_cvt_pk_bf16_f32 v44, v46, v47
	v_cvt_pk_bf16_f32 v45, v48, v49
	v_cvt_pk_bf16_f32 v46, v50, v51
	v_cvt_pk_bf16_f32 v47, v52, v53
	v_cvt_pk_bf16_f32 v48, v54, v55
	v_cvt_pk_bf16_f32 v49, v56, v57
	global_store_dwordx2 v[60:61], v[40:41], off
	global_store_dwordx2 v[60:61], v[44:45], off offset:512
	global_store_dwordx2 v[60:61], v[46:47], off offset:1024
	global_store_dwordx2 v[60:61], v[48:49], off offset:1536
	s_andn2_b64 exec, exec, s[2:3]
	s_cbranch_execnz .Lrow5_top

; DI float bflo(unsigned u) { return __uint_as_float(u << 16); }
; DI float bfhi(unsigned u) { return __uint_as_float(u & 0xffff0000u); }
; DI int lbid() { int b = blockIdx.x; asm volatile("" : "+s"(b)); return b; }
; DI void row_phase(const float* __restrict__ x_in, const u16* __restrict__ y, float c, const float* __restrict__ g_post,
;                   float* __restrict__ x_out, const float* __restrict__ g_pre, u16* __restrict__ hout) {
;     ...
;   for (int row = lbid() * 8 + wid; row < S; row += gridDim.x * 8) {
;     f32x4 xv[4];
; #pragma unroll
;     for (int i = 0; i < 4; ++i) xv[i] = __builtin_nontemporal_load((const f32x4*)(x_in + (size_t)row * DM + 4 * lane + 256 * i));
;     if (y) {
;       f32x4 yv[4];
;       float ss = 0.f;
; #pragma unroll
;       for (int i = 0; i < 4; ++i) {
;         typedef unsigned u32x2_t __attribute__((ext_vector_type(2)));
;         const u32x2_t yb = __builtin_nontemporal_load((const u32x2_t*)(y + (size_t)row * DM + 4 * lane + 256 * i));
;         yv[i] = f32x4{bflo(yb.x), bfhi(yb.x), bflo(yb.y), bfhi(yb.y)};
;         ss += yv[i][0] * yv[i][0] + yv[i][1] * yv[i][1] + yv[i][2] * yv[i][2] + yv[i][3] * yv[i][3];
;       }
;       ss = wave_sum(ss);
;       float r = c * rsqrtf(ss * (1.f / DM) + EPS);
; #pragma unroll
;       for (int i = 0; i < 4; ++i) {
;         f32x4 g = *(const f32x4*)(g_post + 4 * lane + 256 * i);
;         xv[i] += yv[i] * g * r;
;         __builtin_nontemporal_store(xv[i], (f32x4*)(x_out + (size_t)row * DM + 4 * lane + 256 * i));
;       }
.LBB0_776:
	s_or_b64 exec, exec, s[0:1]
	s_barrier
	s_movk_i32 s0, 0x4000
	v_ashrrev_i32_e32 v0, 6, v158
	v_lshl_add_u32 v16, s92, 3, v0
	v_cmp_gt_i32_e32 vcc, s0, v16
	s_and_saveexec_b64 s[0:1], vcc
	s_cbranch_execz .LBB0_779
	v_lshlrev_b32_e32 v0, 2, v158
	v_and_b32_e32 v17, 0xfc, v0
	v_lshlrev_b32_e32 v20, 2, v17
	v_mov_b32_e32 v21, 0
	v_lshl_add_u64 v[0:1], s[38:39], 0, v[20:21]
	s_mov_b64 s[0:1], 0xb000
	v_lshl_add_u64 v[18:19], v[0:1], 0, s[0:1]
	v_add_co_u32_e32 v22, vcc, 0xb000, v0
	s_lshl_b32 s2, s11, 3
	s_nop 0
	v_addc_co_u32_e32 v23, vcc, 0, v1, vcc
	global_load_dwordx4 v[0:3], v[18:19], off offset:1024
	global_load_dwordx4 v[4:7], v[18:19], off offset:2048
	global_load_dwordx4 v[8:11], v[22:23], off
	global_load_dwordx4 v[12:15], v[18:19], off offset:3072
	v_lshl_add_u64 v[18:19], s[22:23], 0, v[20:21]
	v_lshlrev_b32_e32 v20, 1, v17
	v_lshl_add_u64 v[20:21], s[14:15], 0, v[20:21]
	s_mov_b64 s[0:1], 0
	v_mov_b32_e32 v22, 0x358637bd
	s_mov_b32 s3, 0x800000
	s_movk_i32 s4, 0x3fff
	v_mov_b32_e32 v124, v16
	v_ashrrev_i32_e32 v125, 31, v16
	v_lshlrev_b64 v[126:127], 11, v[124:125]
	v_lshl_add_u64 v[126:127], v[20:21], 0, v[126:127]
	global_load_dwordx2 v[100:101], v[126:127], off offset:512 nt
	global_load_dwordx2 v[102:103], v[126:127], off nt
	global_load_dwordx2 v[104:105], v[126:127], off offset:1536 nt
	global_load_dwordx2 v[106:107], v[126:127], off offset:1024 nt
	v_lshlrev_b64 v[126:127], 12, v[124:125]
	v_lshl_add_u64 v[126:127], v[18:19], 0, v[126:127]
	global_load_dwordx4 v[108:111], v[126:127], off nt
	global_load_dwordx4 v[112:115], v[126:127], off offset:1024 nt
	global_load_dwordx4 v[116:119], v[126:127], off offset:2048 nt
	global_load_dwordx4 v[120:123], v[126:127], off offset:3072 nt
	s_waitcnt vmcnt(0)
	s_branch .Lrow6_aw
.Lrow6_top:
	s_waitcnt vmcnt(4)
.Lrow6_aw:
	v_add_u32_e32 v124, s2, v16
	v_ashrrev_i32_e32 v17, 31, v16
	v_lshlrev_b64 v[24:25], 11, v[16:17]
	v_lshl_add_u64 v[24:25], v[20:21], 0, v[24:25]
	v_mov_b64_e32 v[40:41], v[100:101]
	v_mov_b64_e32 v[42:43], v[102:103]
	v_mov_b64_e32 v[44:45], v[104:105]
	v_mov_b64_e32 v[46:47], v[106:107]
	v_lshlrev_b64 v[24:25], 12, v[16:17]
	v_lshl_add_u64 v[48:49], v[18:19], 0, v[24:25]
	v_mov_b64_e32 v[24:25], v[108:109]
	v_mov_b64_e32 v[26:27], v[110:111]
	v_mov_b64_e32 v[28:29], v[112:113]
	v_mov_b64_e32 v[30:31], v[114:115]
	v_mov_b64_e32 v[32:33], v[116:117]
	v_mov_b64_e32 v[34:35], v[118:119]
	v_mov_b64_e32 v[36:37], v[120:121]
	v_mov_b64_e32 v[38:39], v[122:123]
	v_lshrrev_b32_e32 v125, 8, v124
	v_cmp_gt_u32_e64 s[98:99], 64, v125
	s_and_saveexec_b64 s[98:99], s[98:99]
	s_cbranch_execz .Lrow6_nopf
	v_ashrrev_i32_e32 v125, 31, v124
	v_lshlrev_b64 v[126:127], 11, v[124:125]
	v_lshl_add_u64 v[126:127], v[20:21], 0, v[126:127]
	global_load_dwordx2 v[100:101], v[126:127], off offset:512 nt
	global_load_dwordx2 v[102:103], v[126:127], off nt
	global_load_dwordx2 v[104:105], v[126:127], off offset:1536 nt
	global_load_dwordx2 v[106:107], v[126:127], off offset:1024 nt
	v_lshlrev_b64 v[126:127], 12, v[124:125]
	v_lshl_add_u64 v[126:127], v[18:19], 0, v[126:127]
	global_load_dwordx4 v[108:111], v[126:127], off nt
	global_load_dwordx4 v[112:115], v[126:127], off offset:1024 nt
	global_load_dwordx4 v[116:119], v[126:127], off offset:2048 nt
	global_load_dwordx4 v[120:123], v[126:127], off offset:3072 nt
.Lrow6_nopf:
	s_or_b64 exec, exec, s[98:99]
	v_add_u32_e32 v16, s2, v16
	v_cmp_lt_i32_e32 vcc, s4, v16
	s_or_b64 s[0:1], vcc, s[0:1]
	v_and_b32_e32 v53, 0xffff0000, v40
	v_and_b32_e32 v52, 0xffff0000, v42
	v_lshlrev_b32_e32 v51, 16, v40
	v_lshlrev_b32_e32 v50, 16, v42
	v_lshlrev_b32_e32 v54, 16, v43
	v_and_b32_e32 v40, 0xffff0000, v43
	v_lshlrev_b32_e32 v43, 16, v44
	v_lshlrev_b32_e32 v42, 16, v46
	v_and_b32_e32 v57, 0xffff0000, v44
	v_and_b32_e32 v56, 0xffff0000, v46
	v_lshlrev_b32_e32 v58, 16, v47
	v_and_b32_e32 v44, 0xffff0000, v47
	v_pk_mul_f32 v[46:47], v[52:53], v[52:53]
	v_lshlrev_b32_e32 v55, 16, v41
	v_pk_mul_f32 v[60:61], v[56:57], v[56:57]
	v_pk_fma_f32 v[46:47], v[50:51], v[50:51], v[46:47]
	v_and_b32_e32 v41, 0xffff0000, v41
	v_lshlrev_b32_e32 v59, 16, v45
	v_pk_fma_f32 v[60:61], v[42:43], v[42:43], v[60:61]
	v_pk_fma_f32 v[46:47], v[54:55], v[54:55], v[46:47]
	v_and_b32_e32 v45, 0xffff0000, v45
	v_pk_fma_f32 v[60:61], v[58:59], v[58:59], v[60:61]
	v_pk_fma_f32 v[46:47], v[40:41], v[40:41], v[46:47]
	v_pk_fma_f32 v[60:61], v[44:45], v[44:45], v[60:61]
	v_add_f32_e32 v17, v46, v47
	v_add_f32_e32 v17, v17, v60
	v_add_f32_e32 v17, v17, v61
	ds_bpermute_b32 v23, v159, v17
	v_mov_b32_e32 v46, v50
	v_mov_b32_e32 v47, v52
	v_mov_b32_e32 v60, v54
	v_mov_b32_e32 v61, v40
	s_waitcnt lgkmcnt(0)
	v_add_f32_e32 v17, v17, v23
	ds_bpermute_b32 v23, v160, v17
	v_mov_b32_e32 v52, v51
	v_mov_b32_e32 v50, v42
	v_mov_b32_e32 v51, v56
	v_mov_b32_e32 v62, v58
	s_waitcnt lgkmcnt(0)
	v_add_f32_e32 v17, v17, v23
	ds_bpermute_b32 v23, v161, v17
	v_mov_b32_e32 v63, v44
	v_mov_b32_e32 v56, v43
	v_pk_mul_f32 v[42:43], v[8:9], v[46:47]
	v_pk_mul_f32 v[46:47], v[10:11], v[60:61]
	s_waitcnt lgkmcnt(0)
	v_add_f32_e32 v17, v17, v23
	ds_bpermute_b32 v23, v162, v17
	v_mov_b32_e32 v40, v55
	v_mov_b32_e32 v44, v59
	v_pk_mul_f32 v[52:53], v[0:1], v[52:53]
	v_pk_mul_f32 v[50:51], v[4:5], v[50:51]
	s_waitcnt lgkmcnt(0)
	v_add_f32_e32 v17, v17, v23
	ds_bpermute_b32 v23, v163, v17
	v_pk_mul_f32 v[60:61], v[6:7], v[62:63]
	v_pk_mul_f32 v[56:57], v[12:13], v[56:57]
	v_pk_mul_f32 v[40:41], v[2:3], v[40:41]
	v_pk_mul_f32 v[44:45], v[14:15], v[44:45]
	s_waitcnt lgkmcnt(0)
	v_add_f32_e32 v17, v17, v23
	ds_bpermute_b32 v23, v164, v17
	s_waitcnt lgkmcnt(0)
	v_add_f32_e32 v17, v17, v23
	v_fmamk_f32 v17, v17, 0x3a800000, v22
	v_mul_f32_e32 v23, 0x4b800000, v17
	v_cmp_gt_f32_e32 vcc, s3, v17
	s_nop 1
	v_cndmask_b32_e32 v17, v17, v23, vcc
	v_rsq_f32_e32 v17, v17
	s_nop 0
	v_mul_f32_e32 v23, 0x45800000, v17
	v_cndmask_b32_e32 v17, v17, v23, vcc
	v_mul_f32_e32 v54, 0.5, v17
	v_pk_fma_f32 v[26:27], v[46:47], v[54:55], v[26:27] op_sel_hi:[1,0,1]
	v_pk_fma_f32 v[24:25], v[42:43], v[54:55], v[24:25] op_sel_hi:[1,0,1]
	v_pk_fma_f32 v[30:31], v[40:41], v[54:55], v[30:31] op_sel_hi:[1,0,1]
	v_pk_fma_f32 v[28:29], v[52:53], v[54:55], v[28:29] op_sel_hi:[1,0,1]
	v_pk_fma_f32 v[34:35], v[60:61], v[54:55], v[34:35] op_sel_hi:[1,0,1]
	v_pk_fma_f32 v[32:33], v[50:51], v[54:55], v[32:33] op_sel_hi:[1,0,1]
	v_pk_fma_f32 v[38:39], v[44:45], v[54:55], v[38:39] op_sel_hi:[1,0,1]
	v_pk_fma_f32 v[36:37], v[56:57], v[54:55], v[36:37] op_sel_hi:[1,0,1]
	global_store_dwordx4 v[48:49], v[24:27], off nt
	global_store_dwordx4 v[48:49], v[28:31], off offset:1024 nt
	global_store_dwordx4 v[48:49], v[32:35], off offset:2048 nt
	global_store_dwordx4 v[48:49], v[36:39], off offset:3072 nt
	s_andn2_b64 exec, exec, s[0:1]
	s_cbranch_execnz .Lrow6_top
